# residual epilogues of L1 out-proj and L1 down rewritten (batched loads); KV-up GEMM tiles remapped to the CUs that do not run a Q-up tile so the retention scan queue starts earlier
# speedup vs baseline: 1.0549x; 1.0159x over previous
;     DI bool next(int i, Unit& u) const {
;         const long L = (long)i * G + c;
;         u.kq = -1;
;         if (split && L >= nwg) {
;             const int q = (int)(L - nwg); if (q >= 128) return false;
;             const int cu = q >> 2; u.kq = q & 3; u.pm = (cu >> 3) * 9; u.pn = cu & 7; return true;
;         }
;         if (L >= nwg) return false;
;         int wgid = (int)L; { const int q = nwg / NXCD, r = nwg % NXCD, xcd = wgid % NXCD, off = wgid / NXCD; wgid = (xcd < r ? xcd * (q + 1) : r * (q + 1) + (xcd - r) * q) + off; }
;         const int nig = WGM * nN, gid = wgid / nig, fm = gid * WGM, gsz = (nM - fm) < WGM ? (nM - fm) : WGM;
;         int pm = fm + ((wgid % nig) % gsz); u.pn = (wgid % nig) / gsz;
.LBB0_1054:
	s_add_u32 s89, s26, 180
	s_and_b32 s89, s89, 0xff
	s_cmpk_lt_i32 s89, 0xb4
	v_mov_b32_e32 v8, v202
	s_cselect_b64 s[0:1], -1, 0
	v_writelane_b32 v253, s0, 19
	s_cmpk_gt_i32 s89, 0xb3
	v_readfirstlane_b32 s2, v8
	v_writelane_b32 v253, s1, 20
	s_cbranch_scc1 .LBB0_1076
	s_ashr_i32 s3, s26, 31
	s_lshr_b32 s0, s3, 29
	s_add_i32 s4, s89, s0
	s_and_b32 s0, s4, -8
	s_sub_i32 s5, s89, s0
	s_cmp_gt_i32 s5, 3
	s_cbranch_scc0 .LBB0_1057
	s_mul_i32 s0, s5, 22
	s_add_i32 s8, s0, 4
	s_cbranch_execz .LBB0_1058
	s_branch .LBB0_1059

;     DI bool next(int i, Unit& u) const {
;         const long L = (long)i * G + c;
;         u.kq = -1;
;         if (split && L >= nwg) {
;             const int q = (int)(L - nwg); if (q >= 128) return false;
;             const int cu = q >> 2; u.kq = q & 3; u.pm = (cu >> 3) * 9; u.pn = cu & 7; return true;
;         }
;         if (L >= nwg) return false;
;         int wgid = (int)L; { const int q = nwg / NXCD, r = nwg % NXCD, xcd = wgid % NXCD, off = wgid / NXCD; wgid = (xcd < r ? xcd * (q + 1) : r * (q + 1) + (xcd - r) * q) + off; }
.LBB0_1062:
	s_add_i32 s43, s43, 1
	s_mul_i32 s0, s43, s62
	s_mul_hi_u32 s1, s43, s33
	s_add_i32 s1, s1, s0
	s_mul_i32 s0, s43, s33
	s_add_u32 s89, s26, 180
	s_and_b32 s89, s89, 0xff
	s_add_u32 s0, s0, s89
	s_addc_u32 s1, s1, s3
	v_cmp_gt_i64_e64 s[6:7], s[0:1], v[148:149]
	v_cmp_lt_i64_e64 s[8:9], s[0:1], v[146:147]
	s_and_b64 vcc, exec, s[6:7]
	s_cbranch_vccnz .LBB0_1068
	s_ashr_i32 s1, s0, 31
	s_lshr_b32 s1, s1, 29
	s_add_i32 s14, s0, s1
	s_and_b32 s1, s14, -8
	s_sub_i32 s15, s0, s1
	s_cmp_gt_i32 s15, 3
	s_mov_b64 s[0:1], -1
	s_cbranch_scc0 .LBB0_1065
	s_mul_i32 s0, s15, 22
	s_add_i32 s16, s0, 4
	s_mov_b64 s[0:1], 0

;     DI bool next(int i, Unit& u) const {
;         const long L = (long)i * G + c;
;         u.kq = -1;
;         if (split && L >= nwg) {
;             const int q = (int)(L - nwg); if (q >= 128) return false;
;             const int cu = q >> 2; u.kq = q & 3; u.pm = (cu >> 3) * 9; u.pn = cu & 7; return true;
;         }
;         if (L >= nwg) return false;
;         int wgid = (int)L; { const int q = nwg / NXCD, r = nwg % NXCD, xcd = wgid % NXCD, off = wgid / NXCD; wgid = (xcd < r ? xcd * (q + 1) : r * (q + 1) + (xcd - r) * q) + off; }
;         const int nig = WGM * nN, gid = wgid / nig, fm = gid * WGM, gsz = (nM - fm) < WGM ? (nM - fm) : WGM;
;         int pm = fm + ((wgid % nig) % gsz); u.pn = (wgid % nig) / gsz;
.LBB0_2501:
	v_readlane_b32 s0, v253, 19
	v_mov_b32_e32 v8, v202
	v_readlane_b32 s1, v253, 20
	s_andn2_b64 vcc, exec, s[0:1]
	v_readfirstlane_b32 s6, v8
	s_cbranch_vccnz .LBB0_2523
	s_lshr_b32 s0, s85, 29
	s_add_u32 s89, s26, 180
	s_and_b32 s89, s89, 0xff
	s_add_i32 s2, s89, s0
	s_and_b32 s0, s2, -8
	s_sub_i32 s3, s89, s0
	s_cmp_gt_i32 s3, 3
	s_cbranch_scc0 .LBB0_2504
	s_mul_i32 s0, s3, 22
	s_add_i32 s4, s0, 4
	s_cbranch_execz .LBB0_2505
	s_branch .LBB0_2506

;     DI bool next(int i, Unit& u) const {
;         const long L = (long)i * G + c;
;         u.kq = -1;
;         if (split && L >= nwg) {
;             const int q = (int)(L - nwg); if (q >= 128) return false;
;             const int cu = q >> 2; u.kq = q & 3; u.pm = (cu >> 3) * 9; u.pn = cu & 7; return true;
;         }
;         if (L >= nwg) return false;
;         int wgid = (int)L; { const int q = nwg / NXCD, r = nwg % NXCD, xcd = wgid % NXCD, off = wgid / NXCD; wgid = (xcd < r ? xcd * (q + 1) : r * (q + 1) + (xcd - r) * q) + off; }
.LBB0_2509:
	s_add_i32 s42, s42, 1
	s_mul_i32 s0, s42, s84
	s_mul_hi_u32 s1, s42, s33
	s_add_i32 s1, s1, s0
	s_mul_i32 s0, s42, s33
	s_add_u32 s89, s26, 180
	s_and_b32 s89, s89, 0xff
	s_add_u32 s0, s0, s89
	s_addc_u32 s1, s1, s85
	v_cmp_gt_i64_e64 s[2:3], s[0:1], v[148:149]
	v_cmp_lt_i64_e64 s[4:5], s[0:1], v[146:147]
	s_and_b64 vcc, exec, s[2:3]
	s_cbranch_vccnz .LBB0_2515
	s_ashr_i32 s1, s0, 31
	s_lshr_b32 s1, s1, 29
	s_add_i32 s12, s0, s1
	s_and_b32 s1, s12, -8
	s_sub_i32 s13, s0, s1
	s_cmp_gt_i32 s13, 3
	s_mov_b64 s[0:1], -1
	s_cbranch_scc0 .LBB0_2512
	s_mul_i32 s0, s13, 22
	s_add_i32 s14, s0, 4
	s_mov_b64 s[0:1], 0

; template <class Epi, bool PERMROWS = false>
; DI void gemm_phase(LAS unsigned char* lds, const bf16_t* A, int lda, const bf16_t* Bt, int K, const Sched& S, const Epi& E) {
;     ...
;         E(acc, cur, wr, wc, fr, fq);
;         if (!has_next) break;
; #pragma unroll
;         for (int a = 0; a < 2; ++a)
; #pragma unroll
;             for (int b = 0; b < 2; ++b)
; #pragma unroll
;                 for (int m = 0; m < 4; ++m)
; #pragma unroll
;                     for (int n = 0; n < 2; ++n) acc[a][b][m][n] = (f32x4){0.f, 0.f, 0.f, 0.f};
;         cur = nxt; cA = nA; cB = nB; ++ui; nt = cur.kq >= 0 ? ntQ : ntF;
;     }
.LBB0_2743:
	s_and_b64 vcc, exec, s[2:3]
	s_mov_b32 s56, s18
	s_mov_b32 s58, s20
	s_mov_b64 s[60:61], s[36:37]
	s_mov_b64 s[4:5], s[34:35]
	s_cbranch_vccnz .LBB0_2840

; #define G_STAGE(bufoff, gbase, voff) do { _Pragma("unroll") for (int _i = 0; _i < 2; ++_i) \
;         __builtin_amdgcn_global_load_lds((const unsigned*)((const char*)(gbase) + (voff)[_i]), (LAS unsigned*)(lds + (bufoff) + ldsw + _i * 8192), 16, 0, 0); } while (0)
; #define G_LDA(dst, b, h) do { _Pragma("unroll") for (int m = 0; m < 4; ++m) _Pragma("unroll") for (int k = 0; k < 2; ++k) dst[m][k] = *(const LAS bf16x8*)(lds + G_SA(b, h) + aoff + m * 2048 + k * 1024); } while (0)
; #define G_LDB(dst, b, h) do { _Pragma("unroll") for (int n = 0; n < 2; ++n) _Pragma("unroll") for (int k = 0; k < 2; ++k) dst[n][k] = *(const LAS bf16x8*)(lds + G_SB(b, h) + boff + n * 2048 + k * 1024); } while (0)
; #define G_MMA(ai, bj, At, Bt_) do { __builtin_amdgcn_s_setprio(1); _Pragma("unroll") for (int m = 0; m < 4; ++m) _Pragma("unroll") for (int n = 0; n < 2; ++n) _Pragma("unroll") for (int k = 0; k < 2; ++k) \
;         acc[ai][bj][m][n] = __builtin_amdgcn_mfma_f32_16x16x32_bf16(Bt_[n][k], At[m][k], acc[ai][bj][m][n], 0, 0, 0); __builtin_amdgcn_s_setprio(0); } while (0)
; #define G_WAIT_V(n) asm volatile("s_waitcnt vmcnt(" #n ")" ::: "memory")
; #define G_WAIT_L(n) asm volatile("s_waitcnt lgkmcnt(" #n ")" ::: "memory")
; #define G_BAR __builtin_amdgcn_s_barrier()
; #define G_SCHED __builtin_amdgcn_sched_barrier(0)
; template <class Epi, bool PERMROWS = false>
; DI void gemm_phase(LAS unsigned char* lds, const bf16_t* A, int lda, const bf16_t* Bt, int K, const Sched& S, const Epi& E) {
;     ...
;             G_LDB(B0, 0, 0); G_SCHED; G_LDA(At, 0, 0); G_STAGE(G_SA(1, 1), a1 + hstepA, voffA);
;             G_WAIT_L(8); G_BAR; G_WAIT_L(0); G_MMA(0, 0, At, B0); G_BAR; G_SCHED;
;             G_LDB(B1, 0, 1); G_STAGE(G_SB(0, 0), b2, voffB);
;             G_BAR; G_WAIT_L(0); G_MMA(0, 1, At, B1); G_BAR;
;             G_LDA(At, 0, 1); G_STAGE(G_SA(0, 0), a2, voffA);
;             G_BAR; G_WAIT_L(0); G_MMA(1, 0, At, B0); G_BAR; G_SCHED;
;             G_STAGE(G_SB(0, 1), b2 + hstepB, voffB);
;             G_WAIT_V(6); G_BAR; G_MMA(1, 1, At, B1); G_BAR;
;             G_LDB(B0, 1, 0); G_SCHED; G_LDA(At, 1, 0); G_STAGE(G_SA(0, 1), a2 + hstepA, voffA);
;             G_WAIT_L(8); G_BAR; G_WAIT_L(0); G_MMA(0, 0, At, B0); G_BAR; G_SCHED;
.LBB0_2751:
	ds_read_b128 v[128:131], v180
	ds_read_b128 v[132:135], v180 offset:1024
	ds_read_b128 v[136:139], v180 offset:2048
	ds_read_b128 v[140:143], v180 offset:3072
	s_add_u32 s29, s4, 0xfff80080
	s_addc_u32 s60, s5, -1
	s_cmp_eq_u32 s28, 28
	s_cselect_b32 s63, s21, s60
	s_cselect_b32 s62, s42, s29
	s_cselect_b32 s61, s19, s73
	s_cselect_b32 s60, s43, s72
	v_lshl_add_u64 v[168:169], s[4:5], 0, v[150:151]
	s_add_i32 m0, s23, 0xc000
	ds_read_b128 v[156:159], v181
	ds_read_b128 v[160:163], v181 offset:1024
	ds_read_b128 v[164:167], v181 offset:2048
	ds_read_b128 v[184:187], v181 offset:3072
	ds_read_b128 v[188:191], v181 offset:4096
	ds_read_b128 v[192:195], v181 offset:5120
	ds_read_b128 v[196:199], v181 offset:6144
	ds_read_b128 v[204:207], v181 offset:7168
	global_load_lds_dwordx4 v[168:169], off
	v_lshl_add_u64 v[168:169], s[4:5], 0, v[148:149]
	s_add_i32 m0, s23, 0xe000
	s_nop 0
	global_load_lds_dwordx4 v[168:169], off
	s_waitcnt lgkmcnt(8)
	s_barrier
	s_waitcnt lgkmcnt(0)
	s_setprio 1
	s_waitcnt lgkmcnt(0)
	v_mfma_f32_16x16x32_bf16 v[124:127], v[128:131], v[156:159], v[124:127]
	v_mfma_f32_16x16x32_bf16 v[120:123], v[136:139], v[156:159], v[120:123]
	v_mfma_f32_16x16x32_bf16 v[108:111], v[128:131], v[164:167], v[108:111]
	v_mfma_f32_16x16x32_bf16 v[104:107], v[136:139], v[164:167], v[104:107]
	v_mfma_f32_16x16x32_bf16 v[92:95], v[128:131], v[188:191], v[92:95]
	v_mfma_f32_16x16x32_bf16 v[88:91], v[136:139], v[188:191], v[88:91]
	v_mfma_f32_16x16x32_bf16 v[76:79], v[128:131], v[196:199], v[76:79]
	v_mfma_f32_16x16x32_bf16 v[72:75], v[136:139], v[196:199], v[72:75]
	v_mfma_f32_16x16x32_bf16 v[124:127], v[132:135], v[160:163], v[124:127]
	v_mfma_f32_16x16x32_bf16 v[120:123], v[140:143], v[160:163], v[120:123]
	v_mfma_f32_16x16x32_bf16 v[108:111], v[132:135], v[184:187], v[108:111]
	v_mfma_f32_16x16x32_bf16 v[104:107], v[140:143], v[184:187], v[104:107]
	v_mfma_f32_16x16x32_bf16 v[92:95], v[132:135], v[192:195], v[92:95]
	v_mfma_f32_16x16x32_bf16 v[88:91], v[140:143], v[192:195], v[88:91]
	v_mfma_f32_16x16x32_bf16 v[76:79], v[132:135], v[204:207], v[76:79]
	v_mfma_f32_16x16x32_bf16 v[72:75], v[140:143], v[204:207], v[72:75]
	s_setprio 0
	s_barrier
	s_add_i32 s29, s70, s22
	v_lshl_add_u64 v[168:169], s[60:61], 0, v[144:145]
	s_mov_b32 m0, s29
	ds_read_b128 v[208:211], v182
	ds_read_b128 v[212:215], v182 offset:1024
	ds_read_b128 v[216:219], v182 offset:2048
	ds_read_b128 v[220:223], v182 offset:3072
	global_load_lds_dwordx4 v[168:169], off
	v_lshl_add_u64 v[200:201], s[60:61], 0, v[146:147]
	s_add_i32 m0, s29, 0x2000
	s_nop 0
	global_load_lds_dwordx4 v[200:201], off
	s_barrier
	s_waitcnt lgkmcnt(0)
	s_setprio 1
	s_waitcnt lgkmcnt(0)
	v_mfma_f32_16x16x32_bf16 v[116:119], v[208:211], v[156:159], v[116:119]
	v_mfma_f32_16x16x32_bf16 v[112:115], v[216:219], v[156:159], v[112:115]
	v_mfma_f32_16x16x32_bf16 v[100:103], v[208:211], v[164:167], v[100:103]
	v_mfma_f32_16x16x32_bf16 v[96:99], v[216:219], v[164:167], v[96:99]
	v_mfma_f32_16x16x32_bf16 v[84:87], v[208:211], v[188:191], v[84:87]
	v_mfma_f32_16x16x32_bf16 v[80:83], v[216:219], v[188:191], v[80:83]
	v_mfma_f32_16x16x32_bf16 v[68:71], v[208:211], v[196:199], v[68:71]
	v_mfma_f32_16x16x32_bf16 v[64:67], v[216:219], v[196:199], v[64:67]
	v_mfma_f32_16x16x32_bf16 v[116:119], v[212:215], v[160:163], v[116:119]
	v_mfma_f32_16x16x32_bf16 v[112:115], v[220:223], v[160:163], v[112:115]
	v_mfma_f32_16x16x32_bf16 v[100:103], v[212:215], v[184:187], v[100:103]
	v_mfma_f32_16x16x32_bf16 v[96:99], v[220:223], v[184:187], v[96:99]
	v_mfma_f32_16x16x32_bf16 v[84:87], v[212:215], v[192:195], v[84:87]
	v_mfma_f32_16x16x32_bf16 v[80:83], v[220:223], v[192:195], v[80:83]
	v_mfma_f32_16x16x32_bf16 v[68:71], v[212:215], v[204:207], v[68:71]
	v_mfma_f32_16x16x32_bf16 v[64:67], v[220:223], v[204:207], v[64:67]
	s_setprio 0
	s_mov_b32 m0, s23
	v_lshl_add_u64 v[224:225], s[62:63], 0, v[144:145]
	s_barrier
	ds_read_b128 v[156:159], v181 offset:16384
	ds_read_b128 v[160:163], v181 offset:17408
	ds_read_b128 v[164:167], v181 offset:18432
	ds_read_b128 v[184:187], v181 offset:19456
	ds_read_b128 v[188:191], v181 offset:20480
	ds_read_b128 v[192:195], v181 offset:21504
	ds_read_b128 v[196:199], v181 offset:22528
	ds_read_b128 v[204:207], v181 offset:23552
	global_load_lds_dwordx4 v[224:225], off
	v_lshl_add_u64 v[226:227], s[62:63], 0, v[146:147]
	s_mov_b32 m0, s27
	s_nop 0
	global_load_lds_dwordx4 v[226:227], off
	s_barrier
	s_waitcnt lgkmcnt(0)
	s_setprio 1
	s_waitcnt lgkmcnt(0)
	v_mfma_f32_16x16x32_bf16 v[60:63], v[128:131], v[156:159], v[60:63]
	v_mfma_f32_16x16x32_bf16 v[56:59], v[136:139], v[156:159], v[56:59]
	v_mfma_f32_16x16x32_bf16 v[44:47], v[128:131], v[164:167], v[44:47]
	v_mfma_f32_16x16x32_bf16 v[40:43], v[136:139], v[164:167], v[40:43]
	v_mfma_f32_16x16x32_bf16 v[28:31], v[128:131], v[188:191], v[28:31]
	v_mfma_f32_16x16x32_bf16 v[24:27], v[136:139], v[188:191], v[24:27]
	v_mfma_f32_16x16x32_bf16 v[12:15], v[128:131], v[196:199], v[12:15]
	v_mfma_f32_16x16x32_bf16 v[8:11], v[136:139], v[196:199], v[8:11]
	v_mfma_f32_16x16x32_bf16 v[60:63], v[132:135], v[160:163], v[60:63]
	v_mfma_f32_16x16x32_bf16 v[56:59], v[140:143], v[160:163], v[56:59]
	v_mfma_f32_16x16x32_bf16 v[44:47], v[132:135], v[184:187], v[44:47]
	v_mfma_f32_16x16x32_bf16 v[40:43], v[140:143], v[184:187], v[40:43]
	v_mfma_f32_16x16x32_bf16 v[28:31], v[132:135], v[192:195], v[28:31]
	v_mfma_f32_16x16x32_bf16 v[24:27], v[140:143], v[192:195], v[24:27]
	v_mfma_f32_16x16x32_bf16 v[12:15], v[132:135], v[204:207], v[12:15]
	v_mfma_f32_16x16x32_bf16 v[8:11], v[140:143], v[204:207], v[8:11]
	s_setprio 0
	s_barrier
; #define G_STAGE(bufoff, gbase, voff) do { _Pragma("unroll") for (int _i = 0; _i < 2; ++_i) \
;         __builtin_amdgcn_global_load_lds((const unsigned*)((const char*)(gbase) + (voff)[_i]), (LAS unsigned*)(lds + (bufoff) + ldsw + _i * 8192), 16, 0, 0); } while (0)
; #define G_LDA(dst, b, h) do { _Pragma("unroll") for (int m = 0; m < 4; ++m) _Pragma("unroll") for (int k = 0; k < 2; ++k) dst[m][k] = *(const LAS bf16x8*)(lds + G_SA(b, h) + aoff + m * 2048 + k * 1024); } while (0)
; #define G_LDB(dst, b, h) do { _Pragma("unroll") for (int n = 0; n < 2; ++n) _Pragma("unroll") for (int k = 0; k < 2; ++k) dst[n][k] = *(const LAS bf16x8*)(lds + G_SB(b, h) + boff + n * 2048 + k * 1024); } while (0)
; #define G_MMA(ai, bj, At, Bt_) do { __builtin_amdgcn_s_setprio(1); _Pragma("unroll") for (int m = 0; m < 4; ++m) _Pragma("unroll") for (int n = 0; n < 2; ++n) _Pragma("unroll") for (int k = 0; k < 2; ++k) \
;         acc[ai][bj][m][n] = __builtin_amdgcn_mfma_f32_16x16x32_bf16(Bt_[n][k], At[m][k], acc[ai][bj][m][n], 0, 0, 0); __builtin_amdgcn_s_setprio(0); } while (0)
; #define G_WAIT_V(n) asm volatile("s_waitcnt vmcnt(" #n ")" ::: "memory")
; #define G_WAIT_L(n) asm volatile("s_waitcnt lgkmcnt(" #n ")" ::: "memory")
; #define G_BAR __builtin_amdgcn_s_barrier()
; #define G_SCHED __builtin_amdgcn_sched_barrier(0)
; template <class Epi, bool PERMROWS = false>
; DI void gemm_phase(LAS unsigned char* lds, const bf16_t* A, int lda, const bf16_t* Bt, int K, const Sched& S, const Epi& E) {
;     ...
;             G_STAGE(G_SB(0, 1), b2 + hstepB, voffB);
;             G_WAIT_V(6); G_BAR; G_MMA(1, 1, At, B1); G_BAR;
;             G_LDB(B0, 1, 0); G_SCHED; G_LDA(At, 1, 0); G_STAGE(G_SA(0, 1), a2 + hstepA, voffA);
;             G_WAIT_L(8); G_BAR; G_WAIT_L(0); G_MMA(0, 0, At, B0); G_BAR; G_SCHED;
;             G_LDB(B1, 1, 1); G_STAGE(G_SB(1, 0), b3, voffB);
;             G_BAR; G_WAIT_L(0); G_MMA(0, 1, At, B1); G_BAR;
;             G_LDA(At, 1, 1); G_STAGE(G_SA(1, 0), a3, voffA);
;             G_BAR; G_WAIT_L(0); G_MMA(1, 0, At, B0); G_BAR; G_SCHED;
	s_add_u32 s74, s60, 0x80000
	s_addc_u32 s75, s61, 0
	s_add_i32 s29, s71, s22
	v_lshl_add_u64 v[128:129], s[74:75], 0, v[144:145]
	s_mov_b32 m0, s29
	s_nop 0
	global_load_lds_dwordx4 v[128:129], off
	v_lshl_add_u64 v[128:129], s[74:75], 0, v[146:147]
	s_add_i32 m0, s29, 0x2000
	s_nop 0
	global_load_lds_dwordx4 v[128:129], off
	s_waitcnt vmcnt(6)
	s_barrier
	s_setprio 1
	v_mfma_f32_16x16x32_bf16 v[52:55], v[208:211], v[156:159], v[52:55]
	v_mfma_f32_16x16x32_bf16 v[48:51], v[216:219], v[156:159], v[48:51]
	v_mfma_f32_16x16x32_bf16 v[36:39], v[208:211], v[164:167], v[36:39]
	v_mfma_f32_16x16x32_bf16 v[32:35], v[216:219], v[164:167], v[32:35]
	v_mfma_f32_16x16x32_bf16 v[20:23], v[208:211], v[188:191], v[20:23]
	v_mfma_f32_16x16x32_bf16 v[16:19], v[216:219], v[188:191], v[16:19]
	v_mfma_f32_16x16x32_bf16 v[4:7], v[208:211], v[196:199], v[4:7]
	v_mfma_f32_16x16x32_bf16 v[0:3], v[216:219], v[196:199], v[0:3]
	v_mfma_f32_16x16x32_bf16 v[52:55], v[212:215], v[160:163], v[52:55]
	v_mfma_f32_16x16x32_bf16 v[48:51], v[220:223], v[160:163], v[48:51]
	v_mfma_f32_16x16x32_bf16 v[36:39], v[212:215], v[184:187], v[36:39]
	v_mfma_f32_16x16x32_bf16 v[32:35], v[220:223], v[184:187], v[32:35]
	v_mfma_f32_16x16x32_bf16 v[20:23], v[212:215], v[192:195], v[20:23]
	v_mfma_f32_16x16x32_bf16 v[16:19], v[220:223], v[192:195], v[16:19]
	v_mfma_f32_16x16x32_bf16 v[4:7], v[212:215], v[204:207], v[4:7]
	v_mfma_f32_16x16x32_bf16 v[0:3], v[220:223], v[204:207], v[0:3]
	s_setprio 0
	s_add_i32 s29, 0, 0x18000
	v_add_u32_e32 v140, s29, v171
	s_barrier
	ds_read_b128 v[128:131], v140
	ds_read_b128 v[132:135], v140 offset:1024
	ds_read_b128 v[136:139], v140 offset:2048
	ds_read_b128 v[140:143], v140 offset:3072
	s_add_u32 s62, s62, 0x80000
	s_addc_u32 s63, s63, 0
	s_mov_b32 m0, s30
	v_lshl_add_u64 v[208:209], s[62:63], 0, v[144:145]
	ds_read_b128 v[156:159], v181 offset:32768
	ds_read_b128 v[160:163], v181 offset:33792
	ds_read_b128 v[164:167], v181 offset:34816
	ds_read_b128 v[184:187], v181 offset:35840
	ds_read_b128 v[188:191], v181 offset:36864
	ds_read_b128 v[192:195], v181 offset:37888
	ds_read_b128 v[196:199], v181 offset:38912
	ds_read_b128 v[204:207], v181 offset:39936
	global_load_lds_dwordx4 v[208:209], off
	v_lshl_add_u64 v[208:209], s[62:63], 0, v[146:147]
	s_mov_b32 m0, s31
	s_nop 0
	global_load_lds_dwordx4 v[208:209], off
	s_waitcnt lgkmcnt(8)
	s_barrier
	s_waitcnt lgkmcnt(0)
	s_setprio 1
	s_waitcnt lgkmcnt(0)
	v_mfma_f32_16x16x32_bf16 v[124:127], v[128:131], v[156:159], v[124:127]
	v_mfma_f32_16x16x32_bf16 v[120:123], v[136:139], v[156:159], v[120:123]
	v_mfma_f32_16x16x32_bf16 v[108:111], v[128:131], v[164:167], v[108:111]
	v_mfma_f32_16x16x32_bf16 v[104:107], v[136:139], v[164:167], v[104:107]
	v_mfma_f32_16x16x32_bf16 v[92:95], v[128:131], v[188:191], v[92:95]
	v_mfma_f32_16x16x32_bf16 v[88:91], v[136:139], v[188:191], v[88:91]
	v_mfma_f32_16x16x32_bf16 v[76:79], v[128:131], v[196:199], v[76:79]
	v_mfma_f32_16x16x32_bf16 v[72:75], v[136:139], v[196:199], v[72:75]
	v_mfma_f32_16x16x32_bf16 v[124:127], v[132:135], v[160:163], v[124:127]
	v_mfma_f32_16x16x32_bf16 v[120:123], v[140:143], v[160:163], v[120:123]
	v_mfma_f32_16x16x32_bf16 v[108:111], v[132:135], v[184:187], v[108:111]
	v_mfma_f32_16x16x32_bf16 v[104:107], v[140:143], v[184:187], v[104:107]
	v_mfma_f32_16x16x32_bf16 v[92:95], v[132:135], v[192:195], v[92:95]
	v_mfma_f32_16x16x32_bf16 v[88:91], v[140:143], v[192:195], v[88:91]
	v_mfma_f32_16x16x32_bf16 v[76:79], v[132:135], v[204:207], v[76:79]
	v_mfma_f32_16x16x32_bf16 v[72:75], v[140:143], v[204:207], v[72:75]
	s_setprio 0
	s_barrier
	s_add_i32 s62, 0, 0x1c000
	s_add_i32 s29, s29, s22
	v_add_u32_e32 v183, s62, v171
	v_lshl_add_u64 v[168:169], v[168:169], 0, s[0:1]
	s_mov_b32 m0, s29
	ds_read_b128 v[208:211], v183
	ds_read_b128 v[212:215], v183 offset:1024
	ds_read_b128 v[216:219], v183 offset:2048
	ds_read_b128 v[220:223], v183 offset:3072
	global_load_lds_dwordx4 v[168:169], off
	v_lshl_add_u64 v[168:169], v[200:201], 0, s[0:1]
	s_add_i32 m0, s29, 0x2000
	s_nop 0
	global_load_lds_dwordx4 v[168:169], off
	s_barrier
	s_waitcnt lgkmcnt(0)
	s_setprio 1
	s_waitcnt lgkmcnt(0)
	v_mfma_f32_16x16x32_bf16 v[116:119], v[208:211], v[156:159], v[116:119]
	v_mfma_f32_16x16x32_bf16 v[112:115], v[216:219], v[156:159], v[112:115]
	v_mfma_f32_16x16x32_bf16 v[100:103], v[208:211], v[164:167], v[100:103]
	v_mfma_f32_16x16x32_bf16 v[96:99], v[216:219], v[164:167], v[96:99]
	v_mfma_f32_16x16x32_bf16 v[84:87], v[208:211], v[188:191], v[84:87]
	v_mfma_f32_16x16x32_bf16 v[80:83], v[216:219], v[188:191], v[80:83]
	v_mfma_f32_16x16x32_bf16 v[68:71], v[208:211], v[196:199], v[68:71]
	v_mfma_f32_16x16x32_bf16 v[64:67], v[216:219], v[196:199], v[64:67]
	v_mfma_f32_16x16x32_bf16 v[116:119], v[212:215], v[160:163], v[116:119]
	v_mfma_f32_16x16x32_bf16 v[112:115], v[220:223], v[160:163], v[112:115]
	v_mfma_f32_16x16x32_bf16 v[100:103], v[212:215], v[184:187], v[100:103]
	v_mfma_f32_16x16x32_bf16 v[96:99], v[220:223], v[184:187], v[96:99]
	v_mfma_f32_16x16x32_bf16 v[84:87], v[212:215], v[192:195], v[84:87]
	v_mfma_f32_16x16x32_bf16 v[80:83], v[220:223], v[192:195], v[80:83]
	v_mfma_f32_16x16x32_bf16 v[68:71], v[212:215], v[204:207], v[68:71]
	v_mfma_f32_16x16x32_bf16 v[64:67], v[220:223], v[204:207], v[64:67]
	s_setprio 0
	s_mov_b32 m0, s68
	v_lshl_add_u64 v[168:169], v[224:225], 0, s[0:1]
	s_barrier
	ds_read_b128 v[156:159], v181 offset:49152
	ds_read_b128 v[160:163], v181 offset:50176
	ds_read_b128 v[164:167], v181 offset:51200
	ds_read_b128 v[184:187], v181 offset:52224
	ds_read_b128 v[188:191], v181 offset:53248
	ds_read_b128 v[192:195], v181 offset:54272
	ds_read_b128 v[196:199], v181 offset:55296
	ds_read_b128 v[204:207], v181 offset:56320
	global_load_lds_dwordx4 v[168:169], off
	v_lshl_add_u64 v[168:169], v[226:227], 0, s[0:1]
	s_mov_b32 m0, s69
	s_nop 0
	global_load_lds_dwordx4 v[168:169], off
	s_barrier
; #define G_STAGE(bufoff, gbase, voff) do { _Pragma("unroll") for (int _i = 0; _i < 2; ++_i) \
;         __builtin_amdgcn_global_load_lds((const unsigned*)((const char*)(gbase) + (voff)[_i]), (LAS unsigned*)(lds + (bufoff) + ldsw + _i * 8192), 16, 0, 0); } while (0)
; #define G_MMA(ai, bj, At, Bt_) do { __builtin_amdgcn_s_setprio(1); _Pragma("unroll") for (int m = 0; m < 4; ++m) _Pragma("unroll") for (int n = 0; n < 2; ++n) _Pragma("unroll") for (int k = 0; k < 2; ++k) \
;         acc[ai][bj][m][n] = __builtin_amdgcn_mfma_f32_16x16x32_bf16(Bt_[n][k], At[m][k], acc[ai][bj][m][n], 0, 0, 0); __builtin_amdgcn_s_setprio(0); } while (0)
; #define G_WAIT_V(n) asm volatile("s_waitcnt vmcnt(" #n ")" ::: "memory")
; #define G_BAR __builtin_amdgcn_s_barrier()
; template <class Epi, bool PERMROWS = false>
; DI void gemm_phase(LAS unsigned char* lds, const bf16_t* A, int lda, const bf16_t* Bt, int K, const Sched& S, const Epi& E) {
;     ...
;             G_STAGE(G_SB(1, 1), b3 + hstepB, voffB);
;             G_WAIT_V(6); G_BAR; G_MMA(1, 1, At, B1); G_BAR;
;     DI void operator()(const f32x4 (&acc)[2][2][4][2], const Unit& u, int wr, int wc, int fr, int fq) const {
;     ...
;         const float* g = gate + (size_t)s * 12288;
;         const float2* RS = (const float2*)(ws + WS_RSTAT);
; #pragma unroll
;         for (int ai = 0; ai < 2; ++ai)
; #pragma unroll
;             for (int m = 0; m < 4; ++m) {
;                 const int row = u.pm * BM + ai * HALF + wr * 64 + m * 16 + fr;
;                 float mu = 0.f, rs = 1.f;
;                 if (pg) { const float2 st = RS[row]; mu = st.x; rs = st.y; }
	s_waitcnt lgkmcnt(0)
	s_setprio 1
	s_waitcnt lgkmcnt(0)
	v_mfma_f32_16x16x32_bf16 v[60:63], v[128:131], v[156:159], v[60:63]
	v_mfma_f32_16x16x32_bf16 v[56:59], v[136:139], v[156:159], v[56:59]
	v_mfma_f32_16x16x32_bf16 v[44:47], v[128:131], v[164:167], v[44:47]
	v_mfma_f32_16x16x32_bf16 v[40:43], v[136:139], v[164:167], v[40:43]
	v_mfma_f32_16x16x32_bf16 v[28:31], v[128:131], v[188:191], v[28:31]
	v_mfma_f32_16x16x32_bf16 v[24:27], v[136:139], v[188:191], v[24:27]
	v_mfma_f32_16x16x32_bf16 v[12:15], v[128:131], v[196:199], v[12:15]
	v_mfma_f32_16x16x32_bf16 v[8:11], v[136:139], v[196:199], v[8:11]
	v_mfma_f32_16x16x32_bf16 v[60:63], v[132:135], v[160:163], v[60:63]
	v_mfma_f32_16x16x32_bf16 v[56:59], v[140:143], v[160:163], v[56:59]
	v_mfma_f32_16x16x32_bf16 v[44:47], v[132:135], v[184:187], v[44:47]
	v_mfma_f32_16x16x32_bf16 v[40:43], v[140:143], v[184:187], v[40:43]
	v_mfma_f32_16x16x32_bf16 v[28:31], v[132:135], v[192:195], v[28:31]
	v_mfma_f32_16x16x32_bf16 v[24:27], v[140:143], v[192:195], v[24:27]
	v_mfma_f32_16x16x32_bf16 v[12:15], v[132:135], v[204:207], v[12:15]
	v_mfma_f32_16x16x32_bf16 v[8:11], v[140:143], v[204:207], v[8:11]
	s_setprio 0
	s_barrier
	s_add_u32 s60, s60, 0x80080
	s_addc_u32 s61, s61, 0
	s_add_i32 s29, s62, s22
	v_lshl_add_u64 v[128:129], s[60:61], 0, v[144:145]
	s_mov_b32 m0, s29
	s_nop 0
	global_load_lds_dwordx4 v[128:129], off
	v_lshl_add_u64 v[128:129], s[60:61], 0, v[146:147]
	s_add_i32 m0, s29, 0x2000
	s_nop 0
	global_load_lds_dwordx4 v[128:129], off
	s_waitcnt vmcnt(6)
	s_barrier
	s_setprio 1
	v_mfma_f32_16x16x32_bf16 v[52:55], v[208:211], v[156:159], v[52:55]
	v_mfma_f32_16x16x32_bf16 v[48:51], v[216:219], v[156:159], v[48:51]
	v_mfma_f32_16x16x32_bf16 v[36:39], v[208:211], v[164:167], v[36:39]
	v_mfma_f32_16x16x32_bf16 v[32:35], v[216:219], v[164:167], v[32:35]
	v_mfma_f32_16x16x32_bf16 v[20:23], v[208:211], v[188:191], v[20:23]
	v_mfma_f32_16x16x32_bf16 v[16:19], v[216:219], v[188:191], v[16:19]
	v_mfma_f32_16x16x32_bf16 v[4:7], v[208:211], v[196:199], v[4:7]
	v_mfma_f32_16x16x32_bf16 v[0:3], v[216:219], v[196:199], v[0:3]
	v_mfma_f32_16x16x32_bf16 v[52:55], v[212:215], v[160:163], v[52:55]
	v_mfma_f32_16x16x32_bf16 v[48:51], v[220:223], v[160:163], v[48:51]
	v_mfma_f32_16x16x32_bf16 v[36:39], v[212:215], v[184:187], v[36:39]
	v_mfma_f32_16x16x32_bf16 v[32:35], v[220:223], v[184:187], v[32:35]
	v_mfma_f32_16x16x32_bf16 v[20:23], v[212:215], v[192:195], v[20:23]
	v_mfma_f32_16x16x32_bf16 v[16:19], v[220:223], v[192:195], v[16:19]
	v_mfma_f32_16x16x32_bf16 v[4:7], v[212:215], v[204:207], v[4:7]
	v_mfma_f32_16x16x32_bf16 v[0:3], v[220:223], v[204:207], v[0:3]
	s_setprio 0
	s_add_i32 s28, s28, 2
	s_add_u32 s72, s72, 0x100
	s_addc_u32 s73, s73, 0
	s_add_u32 s4, s4, 0x100
	s_addc_u32 s5, s5, 0
	s_cmp_gt_u32 s28, 29
	s_barrier
	s_cbranch_scc0 .LBB0_2751
	v_and_b32_e32 v166, 15, v202
	v_bfe_u32 v167, v202, 8, 1
	v_lshl_add_u32 v166, v167, 6, v166
	v_lshlrev_b32_e32 v183, 3, v166
	v_bfe_u32 v167, v202, 6, 2
	v_lshlrev_b32_e32 v136, 7, v167
	v_bfe_u32 v167, v202, 4, 2
	v_lshl_add_u32 v136, v167, 4, v136
	s_lshl_b32 s29, s56, 10
	v_add_u32_e32 v136, s29, v136
	v_lshl_add_u32 v158, v166, 13, v136
	v_add_u32_e32 v159, 0x20000, v158
	v_add_u32_e32 v160, 0x40000, v158
	v_add_u32_e32 v161, 0x60000, v158
	v_add_u32_e32 v162, 0x100000, v158
	v_add_u32_e32 v163, 0x120000, v158
	v_add_u32_e32 v164, 0x140000, v158
	v_add_u32_e32 v165, 0x160000, v158
	s_mov_b32 s89, 0x3fb504f3
	s_mul_i32 s29, s58, 57
	s_lshr_b32 s29, s29, 9
	s_mul_i32 s32, s29, 9
	s_cmp_lg_u32 s32, s58
	s_cselect_b32 s43, s29, 4
	s_mul_i32 s43, s43, 0xc000
	s_add_u32 s74, s50, 0x48000
	s_addc_u32 s75, s51, 0
	s_add_u32 s74, s74, s43
	s_addc_u32 s75, s75, 0
	global_load_dwordx4 v[220:223], v136, s[74:75] offset:0
	global_load_dwordx4 v[224:227], v136, s[74:75] offset:64
	global_load_dwordx4 v[228:231], v136, s[74:75] offset:512
	global_load_dwordx4 v[232:235], v136, s[74:75] offset:576
	s_add_u32 s74, s44, 0x0
	s_addc_u32 s75, s45, 0
	global_load_dwordx4 v[204:207], v136, s[74:75] offset:0
	global_load_dwordx4 v[208:211], v136, s[74:75] offset:64
	global_load_dwordx4 v[212:215], v136, s[74:75] offset:512
	global_load_dwordx4 v[216:219], v136, s[74:75] offset:576
	s_add_u32 s74, s46, 0x0
	s_addc_u32 s75, s47, 0
	global_load_dwordx4 v[236:239], v136, s[74:75] offset:0
	global_load_dwordx4 v[240:243], v136, s[74:75] offset:64
	global_load_dwordx4 v[244:247], v136, s[74:75] offset:512
	global_load_dwordx4 v[248:251], v136, s[74:75] offset:576
	s_lshl_b32 s29, s58, 11
	s_add_u32 s74, s50, 0x260a0000
	s_addc_u32 s75, s51, 0
	s_add_u32 s74, s74, s29
	s_addc_u32 s75, s75, 0
	global_load_dwordx2 v[128:129], v183, s[74:75] offset:0
	global_load_dwordx2 v[130:131], v183, s[74:75] offset:128
	global_load_dwordx2 v[132:133], v183, s[74:75] offset:256
	global_load_dwordx2 v[134:135], v183, s[74:75] offset:384
	global_load_dwordx2 v[138:139], v183, s[74:75] offset:1024
	global_load_dwordx2 v[140:141], v183, s[74:75] offset:1152
	global_load_dwordx2 v[142:143], v183, s[74:75] offset:1280
	global_load_dwordx2 v[156:157], v183, s[74:75] offset:1408
	s_lshl_b32 s29, s58, 21
	s_add_u32 s72, s50, 0xcba0000
	s_addc_u32 s73, s51, 0
	s_add_u32 s72, s72, s29
	s_addc_u32 s73, s73, 0
	s_waitcnt vmcnt(0)
;     DI void operator()(const f32x4 (&acc)[2][2][4][2], const Unit& u, int wr, int wc, int fr, int fq) const {
;     ...
;         const float* g = gate + (size_t)s * 12288;
;         const float2* RS = (const float2*)(ws + WS_RSTAT);
; #pragma unroll
;         for (int ai = 0; ai < 2; ++ai)
; #pragma unroll
;             for (int m = 0; m < 4; ++m) {
;                 const int row = u.pm * BM + ai * HALF + wr * 64 + m * 16 + fr;
;                 float mu = 0.f, rs = 1.f;
;                 if (pg) { const float2 st = RS[row]; mu = st.x; rs = st.y; }
; #pragma unroll
;                 for (int bj = 0; bj < 2; ++bj)
; #pragma unroll
;                     for (int n = 0; n < 2; ++n) {
;                         const int col = u.pn * BM + bj * HALF + wc * 32 + n * 16 + 4 * fq;
;                         float* xp = X + (size_t)row * DM + col;
;                         f32x4 x4 = *(const f32x4*)xp; const f32x4 g4 = *(const f32x4*)(g + col);
;                         if (pg) x4 = (x4 - mu) * rs * *(const f32x4*)(pg + col) + *(const f32x4*)(pb + col);
;                         *(f32x4*)xp = x4 * ALPHA + g4 * acc[ai][bj][m][n];
	v_mul_f32_e32 v204, s89, v204
	v_mul_f32_e32 v236, s89, v236
	v_mul_f32_e32 v205, s89, v205
	v_mul_f32_e32 v237, s89, v237
	v_mul_f32_e32 v206, s89, v206
	v_mul_f32_e32 v238, s89, v238
	v_mul_f32_e32 v207, s89, v207
	v_mul_f32_e32 v239, s89, v239
	v_mul_f32_e32 v208, s89, v208
	v_mul_f32_e32 v240, s89, v240
	v_mul_f32_e32 v209, s89, v209
	v_mul_f32_e32 v241, s89, v241
	v_mul_f32_e32 v210, s89, v210
	v_mul_f32_e32 v242, s89, v242
	v_mul_f32_e32 v211, s89, v211
	v_mul_f32_e32 v243, s89, v243
	v_mul_f32_e32 v212, s89, v212
	v_mul_f32_e32 v244, s89, v244
	v_mul_f32_e32 v213, s89, v213
	v_mul_f32_e32 v245, s89, v245
	v_mul_f32_e32 v214, s89, v214
	v_mul_f32_e32 v246, s89, v246
	v_mul_f32_e32 v215, s89, v215
	v_mul_f32_e32 v247, s89, v247
	v_mul_f32_e32 v216, s89, v216
	v_mul_f32_e32 v248, s89, v248
	v_mul_f32_e32 v217, s89, v217
	v_mul_f32_e32 v249, s89, v249
	v_mul_f32_e32 v218, s89, v218
	v_mul_f32_e32 v250, s89, v250
	v_mul_f32_e32 v219, s89, v219
	v_mul_f32_e32 v251, s89, v251
	v_fma_f32 v124, v220, v124, v236
	v_fma_f32 v125, v221, v125, v237
	v_fma_f32 v126, v222, v126, v238
	v_fma_f32 v127, v223, v127, v239
	v_fma_f32 v120, v224, v120, v240
	v_fma_f32 v121, v225, v121, v241
	v_fma_f32 v122, v226, v122, v242
	v_fma_f32 v123, v227, v123, v243
	v_fma_f32 v116, v228, v116, v244
	v_fma_f32 v117, v229, v117, v245
	v_fma_f32 v118, v230, v118, v246
	v_fma_f32 v119, v231, v119, v247
	v_fma_f32 v112, v232, v112, v248
	v_fma_f32 v113, v233, v113, v249
	v_fma_f32 v114, v234, v114, v250
	v_fma_f32 v115, v235, v115, v251
	v_fma_f32 v108, v220, v108, v236
	v_fma_f32 v109, v221, v109, v237
	v_fma_f32 v110, v222, v110, v238
	v_fma_f32 v111, v223, v111, v239
	v_fma_f32 v104, v224, v104, v240
	v_fma_f32 v105, v225, v105, v241
	v_fma_f32 v106, v226, v106, v242
	v_fma_f32 v107, v227, v107, v243
	v_fma_f32 v100, v228, v100, v244
	v_fma_f32 v101, v229, v101, v245
	v_fma_f32 v102, v230, v102, v246
	v_fma_f32 v103, v231, v103, v247
	v_fma_f32 v96, v232, v96, v248
	v_fma_f32 v97, v233, v97, v249
	v_fma_f32 v98, v234, v98, v250
	v_fma_f32 v99, v235, v99, v251
	v_fma_f32 v92, v220, v92, v236
	v_fma_f32 v93, v221, v93, v237
	v_fma_f32 v94, v222, v94, v238
	v_fma_f32 v95, v223, v95, v239
	v_fma_f32 v88, v224, v88, v240
	v_fma_f32 v89, v225, v89, v241
	v_fma_f32 v90, v226, v90, v242
	v_fma_f32 v91, v227, v91, v243
	v_fma_f32 v84, v228, v84, v244
	v_fma_f32 v85, v229, v85, v245
	v_fma_f32 v86, v230, v86, v246
	v_fma_f32 v87, v231, v87, v247
	v_fma_f32 v80, v232, v80, v248
	v_fma_f32 v81, v233, v81, v249
	v_fma_f32 v82, v234, v82, v250
	v_fma_f32 v83, v235, v83, v251
	v_fma_f32 v76, v220, v76, v236
	v_fma_f32 v77, v221, v77, v237
	v_fma_f32 v78, v222, v78, v238
	v_fma_f32 v79, v223, v79, v239
	v_fma_f32 v72, v224, v72, v240
	v_fma_f32 v73, v225, v73, v241
	v_fma_f32 v74, v226, v74, v242
	v_fma_f32 v75, v227, v75, v243
	v_fma_f32 v68, v228, v68, v244
	v_fma_f32 v69, v229, v69, v245
	v_fma_f32 v70, v230, v70, v246
	v_fma_f32 v71, v231, v71, v247
	v_fma_f32 v64, v232, v64, v248
	v_fma_f32 v65, v233, v65, v249
	v_fma_f32 v66, v234, v66, v250
	v_fma_f32 v67, v235, v67, v251
	v_fma_f32 v60, v220, v60, v236
	v_fma_f32 v61, v221, v61, v237
	v_fma_f32 v62, v222, v62, v238
	v_fma_f32 v63, v223, v63, v239
	v_fma_f32 v56, v224, v56, v240
	v_fma_f32 v57, v225, v57, v241
	v_fma_f32 v58, v226, v58, v242
	v_fma_f32 v59, v227, v59, v243
	v_fma_f32 v52, v228, v52, v244
	v_fma_f32 v53, v229, v53, v245
	v_fma_f32 v54, v230, v54, v246
	v_fma_f32 v55, v231, v55, v247
	v_fma_f32 v48, v232, v48, v248
	v_fma_f32 v49, v233, v49, v249
	v_fma_f32 v50, v234, v50, v250
	v_fma_f32 v51, v235, v51, v251
	v_fma_f32 v44, v220, v44, v236
	v_fma_f32 v45, v221, v45, v237
	v_fma_f32 v46, v222, v46, v238
	v_fma_f32 v47, v223, v47, v239
	v_fma_f32 v40, v224, v40, v240
	v_fma_f32 v41, v225, v41, v241
	v_fma_f32 v42, v226, v42, v242
	v_fma_f32 v43, v227, v43, v243
	v_fma_f32 v36, v228, v36, v244
	v_fma_f32 v37, v229, v37, v245
	v_fma_f32 v38, v230, v38, v246
	v_fma_f32 v39, v231, v39, v247
	v_fma_f32 v32, v232, v32, v248
	v_fma_f32 v33, v233, v33, v249
	v_fma_f32 v34, v234, v34, v250
	v_fma_f32 v35, v235, v35, v251
	v_fma_f32 v28, v220, v28, v236
	v_fma_f32 v29, v221, v29, v237
	v_fma_f32 v30, v222, v30, v238
	v_fma_f32 v31, v223, v31, v239
	v_fma_f32 v24, v224, v24, v240
	v_fma_f32 v25, v225, v25, v241
	v_fma_f32 v26, v226, v26, v242
	v_fma_f32 v27, v227, v27, v243
	v_fma_f32 v20, v228, v20, v244
	v_fma_f32 v21, v229, v21, v245
	v_fma_f32 v22, v230, v22, v246
	v_fma_f32 v23, v231, v23, v247
	v_fma_f32 v16, v232, v16, v248
	v_fma_f32 v17, v233, v17, v249
	v_fma_f32 v18, v234, v18, v250
	v_fma_f32 v19, v235, v19, v251
	v_fma_f32 v12, v220, v12, v236
	v_fma_f32 v13, v221, v13, v237
	v_fma_f32 v14, v222, v14, v238
	v_fma_f32 v15, v223, v15, v239
	v_fma_f32 v8, v224, v8, v240
	v_fma_f32 v9, v225, v9, v241
	v_fma_f32 v10, v226, v10, v242
	v_fma_f32 v11, v227, v11, v243
	v_fma_f32 v4, v228, v4, v244
	v_fma_f32 v5, v229, v5, v245
	v_fma_f32 v6, v230, v6, v246
	v_fma_f32 v7, v231, v7, v247
	v_fma_f32 v0, v232, v0, v248
	v_fma_f32 v1, v233, v1, v249
	v_fma_f32 v2, v234, v2, v250
	v_fma_f32 v3, v235, v3, v251
	global_load_dwordx4 v[220:223], v158, s[72:73] offset:0
	global_load_dwordx4 v[224:227], v158, s[72:73] offset:64
	global_load_dwordx4 v[228:231], v158, s[72:73] offset:512
	global_load_dwordx4 v[232:235], v158, s[72:73] offset:576
	global_load_dwordx4 v[236:239], v159, s[72:73] offset:0
	global_load_dwordx4 v[240:243], v159, s[72:73] offset:64
	global_load_dwordx4 v[244:247], v159, s[72:73] offset:512
	global_load_dwordx4 v[248:251], v159, s[72:73] offset:576
	s_waitcnt vmcnt(0)
;     DI void operator()(const f32x4 (&acc)[2][2][4][2], const Unit& u, int wr, int wc, int fr, int fq) const {
;     ...
;                 const int row = u.pm * BM + ai * HALF + wr * 64 + m * 16 + fr;
;                 float mu = 0.f, rs = 1.f;
;                 if (pg) { const float2 st = RS[row]; mu = st.x; rs = st.y; }
; #pragma unroll
;                 for (int bj = 0; bj < 2; ++bj)
; #pragma unroll
;                     for (int n = 0; n < 2; ++n) {
;                         const int col = u.pn * BM + bj * HALF + wc * 32 + n * 16 + 4 * fq;
;                         float* xp = X + (size_t)row * DM + col;
;                         f32x4 x4 = *(const f32x4*)xp; const f32x4 g4 = *(const f32x4*)(g + col);
;                         if (pg) x4 = (x4 - mu) * rs * *(const f32x4*)(pg + col) + *(const f32x4*)(pb + col);
;                         *(f32x4*)xp = x4 * ALPHA + g4 * acc[ai][bj][m][n];
	v_sub_f32_e32 v220, v220, v128
	v_mul_f32_e32 v220, v220, v129
	v_fma_f32 v220, v220, v204, v124
	v_sub_f32_e32 v221, v221, v128
	v_mul_f32_e32 v221, v221, v129
	v_fma_f32 v221, v221, v205, v125
	v_sub_f32_e32 v222, v222, v128
	v_mul_f32_e32 v222, v222, v129
	v_fma_f32 v222, v222, v206, v126
	v_sub_f32_e32 v223, v223, v128
	v_mul_f32_e32 v223, v223, v129
	v_fma_f32 v223, v223, v207, v127
	v_sub_f32_e32 v224, v224, v128
	v_mul_f32_e32 v224, v224, v129
	v_fma_f32 v224, v224, v208, v120
	v_sub_f32_e32 v225, v225, v128
	v_mul_f32_e32 v225, v225, v129
	v_fma_f32 v225, v225, v209, v121
	v_sub_f32_e32 v226, v226, v128
	v_mul_f32_e32 v226, v226, v129
	v_fma_f32 v226, v226, v210, v122
	v_sub_f32_e32 v227, v227, v128
	v_mul_f32_e32 v227, v227, v129
	v_fma_f32 v227, v227, v211, v123
	v_sub_f32_e32 v228, v228, v128
	v_mul_f32_e32 v228, v228, v129
	v_fma_f32 v228, v228, v212, v116
	v_sub_f32_e32 v229, v229, v128
	v_mul_f32_e32 v229, v229, v129
	v_fma_f32 v229, v229, v213, v117
	v_sub_f32_e32 v230, v230, v128
	v_mul_f32_e32 v230, v230, v129
	v_fma_f32 v230, v230, v214, v118
	v_sub_f32_e32 v231, v231, v128
	v_mul_f32_e32 v231, v231, v129
	v_fma_f32 v231, v231, v215, v119
	v_sub_f32_e32 v232, v232, v128
	v_mul_f32_e32 v232, v232, v129
	v_fma_f32 v232, v232, v216, v112
	v_sub_f32_e32 v233, v233, v128
	v_mul_f32_e32 v233, v233, v129
	v_fma_f32 v233, v233, v217, v113
	v_sub_f32_e32 v234, v234, v128
	v_mul_f32_e32 v234, v234, v129
	v_fma_f32 v234, v234, v218, v114
	v_sub_f32_e32 v235, v235, v128
	v_mul_f32_e32 v235, v235, v129
	v_fma_f32 v235, v235, v219, v115
	v_sub_f32_e32 v236, v236, v130
	v_mul_f32_e32 v236, v236, v131
	v_fma_f32 v236, v236, v204, v108
	v_sub_f32_e32 v237, v237, v130
	v_mul_f32_e32 v237, v237, v131
	v_fma_f32 v237, v237, v205, v109
	v_sub_f32_e32 v238, v238, v130
	v_mul_f32_e32 v238, v238, v131
	v_fma_f32 v238, v238, v206, v110
	v_sub_f32_e32 v239, v239, v130
	v_mul_f32_e32 v239, v239, v131
	v_fma_f32 v239, v239, v207, v111
	v_sub_f32_e32 v240, v240, v130
	v_mul_f32_e32 v240, v240, v131
	v_fma_f32 v240, v240, v208, v104
	v_sub_f32_e32 v241, v241, v130
	v_mul_f32_e32 v241, v241, v131
	v_fma_f32 v241, v241, v209, v105
	v_sub_f32_e32 v242, v242, v130
	v_mul_f32_e32 v242, v242, v131
	v_fma_f32 v242, v242, v210, v106
	v_sub_f32_e32 v243, v243, v130
	v_mul_f32_e32 v243, v243, v131
	v_fma_f32 v243, v243, v211, v107
	v_sub_f32_e32 v244, v244, v130
	v_mul_f32_e32 v244, v244, v131
	v_fma_f32 v244, v244, v212, v100
	v_sub_f32_e32 v245, v245, v130
	v_mul_f32_e32 v245, v245, v131
	v_fma_f32 v245, v245, v213, v101
	v_sub_f32_e32 v246, v246, v130
	v_mul_f32_e32 v246, v246, v131
	v_fma_f32 v246, v246, v214, v102
	v_sub_f32_e32 v247, v247, v130
	v_mul_f32_e32 v247, v247, v131
	v_fma_f32 v247, v247, v215, v103
	v_sub_f32_e32 v248, v248, v130
	v_mul_f32_e32 v248, v248, v131
	v_fma_f32 v248, v248, v216, v96
	v_sub_f32_e32 v249, v249, v130
	v_mul_f32_e32 v249, v249, v131
	v_fma_f32 v249, v249, v217, v97
	v_sub_f32_e32 v250, v250, v130
	v_mul_f32_e32 v250, v250, v131
	v_fma_f32 v250, v250, v218, v98
	v_sub_f32_e32 v251, v251, v130
	v_mul_f32_e32 v251, v251, v131
	v_fma_f32 v251, v251, v219, v99
	global_load_dwordx4 v[124:127], v160, s[72:73] offset:0
	global_load_dwordx4 v[120:123], v160, s[72:73] offset:64
	global_load_dwordx4 v[116:119], v160, s[72:73] offset:512
	global_load_dwordx4 v[112:115], v160, s[72:73] offset:576
	global_load_dwordx4 v[108:111], v161, s[72:73] offset:0
	global_load_dwordx4 v[104:107], v161, s[72:73] offset:64
	global_load_dwordx4 v[100:103], v161, s[72:73] offset:512
	global_load_dwordx4 v[96:99], v161, s[72:73] offset:576
	global_store_dwordx4 v158, v[220:223], s[72:73] offset:0
	global_store_dwordx4 v158, v[224:227], s[72:73] offset:64
	global_store_dwordx4 v158, v[228:231], s[72:73] offset:512
	global_store_dwordx4 v158, v[232:235], s[72:73] offset:576
	global_store_dwordx4 v159, v[236:239], s[72:73] offset:0
	global_store_dwordx4 v159, v[240:243], s[72:73] offset:64
	global_store_dwordx4 v159, v[244:247], s[72:73] offset:512
	global_store_dwordx4 v159, v[248:251], s[72:73] offset:576
	global_load_dwordx4 v[220:223], v162, s[72:73] offset:0
	global_load_dwordx4 v[224:227], v162, s[72:73] offset:64
	global_load_dwordx4 v[228:231], v162, s[72:73] offset:512
	global_load_dwordx4 v[232:235], v162, s[72:73] offset:576
	global_load_dwordx4 v[236:239], v163, s[72:73] offset:0
	global_load_dwordx4 v[240:243], v163, s[72:73] offset:64
	global_load_dwordx4 v[244:247], v163, s[72:73] offset:512
	global_load_dwordx4 v[248:251], v163, s[72:73] offset:576
	s_waitcnt vmcnt(0)
;     DI void operator()(const f32x4 (&acc)[2][2][4][2], const Unit& u, int wr, int wc, int fr, int fq) const {
;     ...
;         const float* g = gate + (size_t)s * 12288;
;         const float2* RS = (const float2*)(ws + WS_RSTAT);
; #pragma unroll
;         for (int ai = 0; ai < 2; ++ai)
; #pragma unroll
;             for (int m = 0; m < 4; ++m) {
;                 const int row = u.pm * BM + ai * HALF + wr * 64 + m * 16 + fr;
;                 float mu = 0.f, rs = 1.f;
;                 if (pg) { const float2 st = RS[row]; mu = st.x; rs = st.y; }
; #pragma unroll
;                 for (int bj = 0; bj < 2; ++bj)
; #pragma unroll
;                     for (int n = 0; n < 2; ++n) {
;                         const int col = u.pn * BM + bj * HALF + wc * 32 + n * 16 + 4 * fq;
;                         float* xp = X + (size_t)row * DM + col;
;                         f32x4 x4 = *(const f32x4*)xp; const f32x4 g4 = *(const f32x4*)(g + col);
;                         if (pg) x4 = (x4 - mu) * rs * *(const f32x4*)(pg + col) + *(const f32x4*)(pb + col);
;                         *(f32x4*)xp = x4 * ALPHA + g4 * acc[ai][bj][m][n];
;                     }
	v_sub_f32_e32 v124, v124, v132
	v_mul_f32_e32 v124, v124, v133
	v_fma_f32 v124, v124, v204, v92
	v_sub_f32_e32 v125, v125, v132
	v_mul_f32_e32 v125, v125, v133
	v_fma_f32 v125, v125, v205, v93
	v_sub_f32_e32 v126, v126, v132
	v_mul_f32_e32 v126, v126, v133
	v_fma_f32 v126, v126, v206, v94
	v_sub_f32_e32 v127, v127, v132
	v_mul_f32_e32 v127, v127, v133
	v_fma_f32 v127, v127, v207, v95
	v_sub_f32_e32 v120, v120, v132
	v_mul_f32_e32 v120, v120, v133
	v_fma_f32 v120, v120, v208, v88
	v_sub_f32_e32 v121, v121, v132
	v_mul_f32_e32 v121, v121, v133
	v_fma_f32 v121, v121, v209, v89
	v_sub_f32_e32 v122, v122, v132
	v_mul_f32_e32 v122, v122, v133
	v_fma_f32 v122, v122, v210, v90
	v_sub_f32_e32 v123, v123, v132
	v_mul_f32_e32 v123, v123, v133
	v_fma_f32 v123, v123, v211, v91
	v_sub_f32_e32 v116, v116, v132
	v_mul_f32_e32 v116, v116, v133
	v_fma_f32 v116, v116, v212, v84
	v_sub_f32_e32 v117, v117, v132
	v_mul_f32_e32 v117, v117, v133
	v_fma_f32 v117, v117, v213, v85
	v_sub_f32_e32 v118, v118, v132
	v_mul_f32_e32 v118, v118, v133
	v_fma_f32 v118, v118, v214, v86
	v_sub_f32_e32 v119, v119, v132
	v_mul_f32_e32 v119, v119, v133
	v_fma_f32 v119, v119, v215, v87
	v_sub_f32_e32 v112, v112, v132
	v_mul_f32_e32 v112, v112, v133
	v_fma_f32 v112, v112, v216, v80
	v_sub_f32_e32 v113, v113, v132
	v_mul_f32_e32 v113, v113, v133
	v_fma_f32 v113, v113, v217, v81
	v_sub_f32_e32 v114, v114, v132
	v_mul_f32_e32 v114, v114, v133
	v_fma_f32 v114, v114, v218, v82
	v_sub_f32_e32 v115, v115, v132
	v_mul_f32_e32 v115, v115, v133
	v_fma_f32 v115, v115, v219, v83
	v_sub_f32_e32 v108, v108, v134
	v_mul_f32_e32 v108, v108, v135
	v_fma_f32 v108, v108, v204, v76
	v_sub_f32_e32 v109, v109, v134
	v_mul_f32_e32 v109, v109, v135
	v_fma_f32 v109, v109, v205, v77
	v_sub_f32_e32 v110, v110, v134
	v_mul_f32_e32 v110, v110, v135
	v_fma_f32 v110, v110, v206, v78
	v_sub_f32_e32 v111, v111, v134
	v_mul_f32_e32 v111, v111, v135
	v_fma_f32 v111, v111, v207, v79
	v_sub_f32_e32 v104, v104, v134
	v_mul_f32_e32 v104, v104, v135
	v_fma_f32 v104, v104, v208, v72
	v_sub_f32_e32 v105, v105, v134
	v_mul_f32_e32 v105, v105, v135
	v_fma_f32 v105, v105, v209, v73
	v_sub_f32_e32 v106, v106, v134
	v_mul_f32_e32 v106, v106, v135
	v_fma_f32 v106, v106, v210, v74
	v_sub_f32_e32 v107, v107, v134
	v_mul_f32_e32 v107, v107, v135
	v_fma_f32 v107, v107, v211, v75
	v_sub_f32_e32 v100, v100, v134
	v_mul_f32_e32 v100, v100, v135
	v_fma_f32 v100, v100, v212, v68
	v_sub_f32_e32 v101, v101, v134
	v_mul_f32_e32 v101, v101, v135
	v_fma_f32 v101, v101, v213, v69
	v_sub_f32_e32 v102, v102, v134
	v_mul_f32_e32 v102, v102, v135
	v_fma_f32 v102, v102, v214, v70
	v_sub_f32_e32 v103, v103, v134
	v_mul_f32_e32 v103, v103, v135
	v_fma_f32 v103, v103, v215, v71
	v_sub_f32_e32 v96, v96, v134
	v_mul_f32_e32 v96, v96, v135
	v_fma_f32 v96, v96, v216, v64
	v_sub_f32_e32 v97, v97, v134
	v_mul_f32_e32 v97, v97, v135
	v_fma_f32 v97, v97, v217, v65
	v_sub_f32_e32 v98, v98, v134
	v_mul_f32_e32 v98, v98, v135
	v_fma_f32 v98, v98, v218, v66
	v_sub_f32_e32 v99, v99, v134
	v_mul_f32_e32 v99, v99, v135
	v_fma_f32 v99, v99, v219, v67
	v_sub_f32_e32 v220, v220, v138
	v_mul_f32_e32 v220, v220, v139
	v_fma_f32 v220, v220, v204, v60
	v_sub_f32_e32 v221, v221, v138
	v_mul_f32_e32 v221, v221, v139
	v_fma_f32 v221, v221, v205, v61
	v_sub_f32_e32 v222, v222, v138
	v_mul_f32_e32 v222, v222, v139
	v_fma_f32 v222, v222, v206, v62
	v_sub_f32_e32 v223, v223, v138
	v_mul_f32_e32 v223, v223, v139
	v_fma_f32 v223, v223, v207, v63
	v_sub_f32_e32 v224, v224, v138
	v_mul_f32_e32 v224, v224, v139
	v_fma_f32 v224, v224, v208, v56
	v_sub_f32_e32 v225, v225, v138
	v_mul_f32_e32 v225, v225, v139
	v_fma_f32 v225, v225, v209, v57
	v_sub_f32_e32 v226, v226, v138
	v_mul_f32_e32 v226, v226, v139
	v_fma_f32 v226, v226, v210, v58
	v_sub_f32_e32 v227, v227, v138
	v_mul_f32_e32 v227, v227, v139
	v_fma_f32 v227, v227, v211, v59
	v_sub_f32_e32 v228, v228, v138
	v_mul_f32_e32 v228, v228, v139
	v_fma_f32 v228, v228, v212, v52
	v_sub_f32_e32 v229, v229, v138
	v_mul_f32_e32 v229, v229, v139
	v_fma_f32 v229, v229, v213, v53
	v_sub_f32_e32 v230, v230, v138
	v_mul_f32_e32 v230, v230, v139
	v_fma_f32 v230, v230, v214, v54
	v_sub_f32_e32 v231, v231, v138
	v_mul_f32_e32 v231, v231, v139
	v_fma_f32 v231, v231, v215, v55
	v_sub_f32_e32 v232, v232, v138
	v_mul_f32_e32 v232, v232, v139
	v_fma_f32 v232, v232, v216, v48
	v_sub_f32_e32 v233, v233, v138
	v_mul_f32_e32 v233, v233, v139
	v_fma_f32 v233, v233, v217, v49
	v_sub_f32_e32 v234, v234, v138
	v_mul_f32_e32 v234, v234, v139
	v_fma_f32 v234, v234, v218, v50
	v_sub_f32_e32 v235, v235, v138
	v_mul_f32_e32 v235, v235, v139
	v_fma_f32 v235, v235, v219, v51
	v_sub_f32_e32 v236, v236, v140
	v_mul_f32_e32 v236, v236, v141
	v_fma_f32 v236, v236, v204, v44
	v_sub_f32_e32 v237, v237, v140
	v_mul_f32_e32 v237, v237, v141
	v_fma_f32 v237, v237, v205, v45
	v_sub_f32_e32 v238, v238, v140
	v_mul_f32_e32 v238, v238, v141
	v_fma_f32 v238, v238, v206, v46
	v_sub_f32_e32 v239, v239, v140
	v_mul_f32_e32 v239, v239, v141
	v_fma_f32 v239, v239, v207, v47
	v_sub_f32_e32 v240, v240, v140
	v_mul_f32_e32 v240, v240, v141
	v_fma_f32 v240, v240, v208, v40
	v_sub_f32_e32 v241, v241, v140
	v_mul_f32_e32 v241, v241, v141
	v_fma_f32 v241, v241, v209, v41
	v_sub_f32_e32 v242, v242, v140
	v_mul_f32_e32 v242, v242, v141
	v_fma_f32 v242, v242, v210, v42
	v_sub_f32_e32 v243, v243, v140
	v_mul_f32_e32 v243, v243, v141
	v_fma_f32 v243, v243, v211, v43
	v_sub_f32_e32 v244, v244, v140
	v_mul_f32_e32 v244, v244, v141
	v_fma_f32 v244, v244, v212, v36
;     DI void operator()(const f32x4 (&acc)[2][2][4][2], const Unit& u, int wr, int wc, int fr, int fq) const {
;     ...
;         const float* g = gate + (size_t)s * 12288;
;         const float2* RS = (const float2*)(ws + WS_RSTAT);
; #pragma unroll
;         for (int ai = 0; ai < 2; ++ai)
; #pragma unroll
;             for (int m = 0; m < 4; ++m) {
;                 const int row = u.pm * BM + ai * HALF + wr * 64 + m * 16 + fr;
;                 float mu = 0.f, rs = 1.f;
;                 if (pg) { const float2 st = RS[row]; mu = st.x; rs = st.y; }
; #pragma unroll
;                 for (int bj = 0; bj < 2; ++bj)
; #pragma unroll
;                     for (int n = 0; n < 2; ++n) {
;                         const int col = u.pn * BM + bj * HALF + wc * 32 + n * 16 + 4 * fq;
;                         float* xp = X + (size_t)row * DM + col;
;                         f32x4 x4 = *(const f32x4*)xp; const f32x4 g4 = *(const f32x4*)(g + col);
;                         if (pg) x4 = (x4 - mu) * rs * *(const f32x4*)(pg + col) + *(const f32x4*)(pb + col);
;                         *(f32x4*)xp = x4 * ALPHA + g4 * acc[ai][bj][m][n];
;                     }
	v_sub_f32_e32 v245, v245, v140
	v_mul_f32_e32 v245, v245, v141
	v_fma_f32 v245, v245, v213, v37
	v_sub_f32_e32 v246, v246, v140
	v_mul_f32_e32 v246, v246, v141
	v_fma_f32 v246, v246, v214, v38
	v_sub_f32_e32 v247, v247, v140
	v_mul_f32_e32 v247, v247, v141
	v_fma_f32 v247, v247, v215, v39
	v_sub_f32_e32 v248, v248, v140
	v_mul_f32_e32 v248, v248, v141
	v_fma_f32 v248, v248, v216, v32
	v_sub_f32_e32 v249, v249, v140
	v_mul_f32_e32 v249, v249, v141
	v_fma_f32 v249, v249, v217, v33
	v_sub_f32_e32 v250, v250, v140
	v_mul_f32_e32 v250, v250, v141
	v_fma_f32 v250, v250, v218, v34
	v_sub_f32_e32 v251, v251, v140
	v_mul_f32_e32 v251, v251, v141
	v_fma_f32 v251, v251, v219, v35
	global_load_dwordx4 v[92:95], v164, s[72:73] offset:0
	global_load_dwordx4 v[88:91], v164, s[72:73] offset:64
	global_load_dwordx4 v[84:87], v164, s[72:73] offset:512
	global_load_dwordx4 v[80:83], v164, s[72:73] offset:576
	global_load_dwordx4 v[76:79], v165, s[72:73] offset:0
	global_load_dwordx4 v[72:75], v165, s[72:73] offset:64
	global_load_dwordx4 v[68:71], v165, s[72:73] offset:512
	global_load_dwordx4 v[64:67], v165, s[72:73] offset:576
	global_store_dwordx4 v160, v[124:127], s[72:73] offset:0
	global_store_dwordx4 v160, v[120:123], s[72:73] offset:64
	global_store_dwordx4 v160, v[116:119], s[72:73] offset:512
	global_store_dwordx4 v160, v[112:115], s[72:73] offset:576
	global_store_dwordx4 v161, v[108:111], s[72:73] offset:0
	global_store_dwordx4 v161, v[104:107], s[72:73] offset:64
	global_store_dwordx4 v161, v[100:103], s[72:73] offset:512
	global_store_dwordx4 v161, v[96:99], s[72:73] offset:576
	global_store_dwordx4 v162, v[220:223], s[72:73] offset:0
	global_store_dwordx4 v162, v[224:227], s[72:73] offset:64
	global_store_dwordx4 v162, v[228:231], s[72:73] offset:512
	global_store_dwordx4 v162, v[232:235], s[72:73] offset:576
	global_store_dwordx4 v163, v[236:239], s[72:73] offset:0
	global_store_dwordx4 v163, v[240:243], s[72:73] offset:64
	global_store_dwordx4 v163, v[244:247], s[72:73] offset:512
	global_store_dwordx4 v163, v[248:251], s[72:73] offset:576
	s_waitcnt vmcnt(16)
	v_sub_f32_e32 v92, v92, v142
	v_mul_f32_e32 v92, v92, v143
	v_fma_f32 v92, v92, v204, v28
	v_sub_f32_e32 v93, v93, v142
	v_mul_f32_e32 v93, v93, v143
	v_fma_f32 v93, v93, v205, v29
	v_sub_f32_e32 v94, v94, v142
	v_mul_f32_e32 v94, v94, v143
	v_fma_f32 v94, v94, v206, v30
	v_sub_f32_e32 v95, v95, v142
	v_mul_f32_e32 v95, v95, v143
	v_fma_f32 v95, v95, v207, v31
	v_sub_f32_e32 v88, v88, v142
	v_mul_f32_e32 v88, v88, v143
	v_fma_f32 v88, v88, v208, v24
	v_sub_f32_e32 v89, v89, v142
	v_mul_f32_e32 v89, v89, v143
	v_fma_f32 v89, v89, v209, v25
	v_sub_f32_e32 v90, v90, v142
	v_mul_f32_e32 v90, v90, v143
	v_fma_f32 v90, v90, v210, v26
	v_sub_f32_e32 v91, v91, v142
	v_mul_f32_e32 v91, v91, v143
	v_fma_f32 v91, v91, v211, v27
	v_sub_f32_e32 v84, v84, v142
	v_mul_f32_e32 v84, v84, v143
	v_fma_f32 v84, v84, v212, v20
	v_sub_f32_e32 v85, v85, v142
	v_mul_f32_e32 v85, v85, v143
	v_fma_f32 v85, v85, v213, v21
	v_sub_f32_e32 v86, v86, v142
	v_mul_f32_e32 v86, v86, v143
	v_fma_f32 v86, v86, v214, v22
	v_sub_f32_e32 v87, v87, v142
	v_mul_f32_e32 v87, v87, v143
	v_fma_f32 v87, v87, v215, v23
	v_sub_f32_e32 v80, v80, v142
	v_mul_f32_e32 v80, v80, v143
	v_fma_f32 v80, v80, v216, v16
	v_sub_f32_e32 v81, v81, v142
	v_mul_f32_e32 v81, v81, v143
	v_fma_f32 v81, v81, v217, v17
	v_sub_f32_e32 v82, v82, v142
	v_mul_f32_e32 v82, v82, v143
	v_fma_f32 v82, v82, v218, v18
	v_sub_f32_e32 v83, v83, v142
	v_mul_f32_e32 v83, v83, v143
	v_fma_f32 v83, v83, v219, v19
	v_sub_f32_e32 v76, v76, v156
	v_mul_f32_e32 v76, v76, v157
	v_fma_f32 v76, v76, v204, v12
	v_sub_f32_e32 v77, v77, v156
	v_mul_f32_e32 v77, v77, v157
	v_fma_f32 v77, v77, v205, v13
	v_sub_f32_e32 v78, v78, v156
	v_mul_f32_e32 v78, v78, v157
	v_fma_f32 v78, v78, v206, v14
	v_sub_f32_e32 v79, v79, v156
	v_mul_f32_e32 v79, v79, v157
	v_fma_f32 v79, v79, v207, v15
	v_sub_f32_e32 v72, v72, v156
	v_mul_f32_e32 v72, v72, v157
	v_fma_f32 v72, v72, v208, v8
	v_sub_f32_e32 v73, v73, v156
	v_mul_f32_e32 v73, v73, v157
	v_fma_f32 v73, v73, v209, v9
	v_sub_f32_e32 v74, v74, v156
	v_mul_f32_e32 v74, v74, v157
	v_fma_f32 v74, v74, v210, v10
	v_sub_f32_e32 v75, v75, v156
	v_mul_f32_e32 v75, v75, v157
	v_fma_f32 v75, v75, v211, v11
	v_sub_f32_e32 v68, v68, v156
	v_mul_f32_e32 v68, v68, v157
	v_fma_f32 v68, v68, v212, v4
	v_sub_f32_e32 v69, v69, v156
	v_mul_f32_e32 v69, v69, v157
	v_fma_f32 v69, v69, v213, v5
	v_sub_f32_e32 v70, v70, v156
	v_mul_f32_e32 v70, v70, v157
	v_fma_f32 v70, v70, v214, v6
	v_sub_f32_e32 v71, v71, v156
	v_mul_f32_e32 v71, v71, v157
	v_fma_f32 v71, v71, v215, v7
	v_sub_f32_e32 v64, v64, v156
	v_mul_f32_e32 v64, v64, v157
	v_fma_f32 v64, v64, v216, v0
	v_sub_f32_e32 v65, v65, v156
	v_mul_f32_e32 v65, v65, v157
	v_fma_f32 v65, v65, v217, v1
	v_sub_f32_e32 v66, v66, v156
	v_mul_f32_e32 v66, v66, v157
	v_fma_f32 v66, v66, v218, v2
	v_sub_f32_e32 v67, v67, v156
	v_mul_f32_e32 v67, v67, v157
	v_fma_f32 v67, v67, v219, v3
	global_store_dwordx4 v164, v[92:95], s[72:73] offset:0
	global_store_dwordx4 v164, v[88:91], s[72:73] offset:64
	global_store_dwordx4 v164, v[84:87], s[72:73] offset:512
	global_store_dwordx4 v164, v[80:83], s[72:73] offset:576
	global_store_dwordx4 v165, v[76:79], s[72:73] offset:0
	global_store_dwordx4 v165, v[72:75], s[72:73] offset:64
	global_store_dwordx4 v165, v[68:71], s[72:73] offset:512
	global_store_dwordx4 v165, v[64:67], s[72:73] offset:576
	s_branch .LBB0_2743

; #define G_STAGE(bufoff, gbase, voff) do { _Pragma("unroll") for (int _i = 0; _i < 2; ++_i) \
;         __builtin_amdgcn_global_load_lds((const unsigned*)((const char*)(gbase) + (voff)[_i]), (LAS unsigned*)(lds + (bufoff) + ldsw + _i * 8192), 16, 0, 0); } while (0)
; #define G_LDA(dst, b, h) do { _Pragma("unroll") for (int m = 0; m < 4; ++m) _Pragma("unroll") for (int k = 0; k < 2; ++k) dst[m][k] = *(const LAS bf16x8*)(lds + G_SA(b, h) + aoff + m * 2048 + k * 1024); } while (0)
; #define G_LDB(dst, b, h) do { _Pragma("unroll") for (int n = 0; n < 2; ++n) _Pragma("unroll") for (int k = 0; k < 2; ++k) dst[n][k] = *(const LAS bf16x8*)(lds + G_SB(b, h) + boff + n * 2048 + k * 1024); } while (0)
; #define G_MMA(ai, bj, At, Bt_) do { __builtin_amdgcn_s_setprio(1); _Pragma("unroll") for (int m = 0; m < 4; ++m) _Pragma("unroll") for (int n = 0; n < 2; ++n) _Pragma("unroll") for (int k = 0; k < 2; ++k) \
;         acc[ai][bj][m][n] = __builtin_amdgcn_mfma_f32_16x16x32_bf16(Bt_[n][k], At[m][k], acc[ai][bj][m][n], 0, 0, 0); __builtin_amdgcn_s_setprio(0); } while (0)
; #define G_WAIT_V(n) asm volatile("s_waitcnt vmcnt(" #n ")" ::: "memory")
; #define G_WAIT_L(n) asm volatile("s_waitcnt lgkmcnt(" #n ")" ::: "memory")
; #define G_BAR __builtin_amdgcn_s_barrier()
; #define G_SCHED __builtin_amdgcn_sched_barrier(0)
; template <class Epi, bool PERMROWS = false>
; DI void gemm_phase(LAS unsigned char* lds, const bf16_t* A, int lda, const bf16_t* Bt, int K, const Sched& S, const Epi& E) {
;     ...
;             const char* a1 = cA + (size_t)(t + 1) * kstep;
;             const char* a2 = last ? nA : cA + (size_t)(t + 2) * kstep; const char* b2 = last ? nB : cB + (size_t)(t + 2) * kstep;
;             const char* a3 = a2 + kstep; const char* b3 = b2 + kstep;
;             G_LDB(B0, 0, 0); G_SCHED; G_LDA(At, 0, 0); G_STAGE(G_SA(1, 1), a1 + hstepA, voffA);
;             G_WAIT_L(8); G_BAR; G_WAIT_L(0); G_MMA(0, 0, At, B0); G_BAR; G_SCHED;
;             G_LDB(B1, 0, 1); G_STAGE(G_SB(0, 0), b2, voffB);
;             G_BAR; G_WAIT_L(0); G_MMA(0, 1, At, B1); G_BAR;
;             G_LDA(At, 0, 1); G_STAGE(G_SA(0, 0), a2, voffA);
;             G_BAR; G_WAIT_L(0); G_MMA(1, 0, At, B0); G_BAR; G_SCHED;
;             G_STAGE(G_SB(0, 1), b2 + hstepB, voffB);
;             G_WAIT_V(6); G_BAR; G_MMA(1, 1, At, B1); G_BAR;
.LBB0_3113:
	ds_read_b128 v[140:143], v160
	ds_read_b128 v[144:147], v160 offset:1024
	ds_read_b128 v[148:151], v160 offset:2048
	ds_read_b128 v[164:167], v160 offset:3072
	s_add_u32 s22, s20, 0x100
	s_addc_u32 s23, s21, 0
	s_cmpk_eq_i32 s29, 0x54
	s_cselect_b32 s35, s5, s23
	s_cselect_b32 s34, s4, s22
	s_cselect_b32 s31, s1, s28
	s_cselect_b32 s30, s0, s61
	v_lshl_add_u64 v[152:153], s[20:21], 0, v[134:135]
	s_add_i32 m0, s38, 0xc000
	ds_read_b128 v[168:171], v161
	ds_read_b128 v[172:175], v161 offset:1024
	ds_read_b128 v[176:179], v161 offset:2048
	ds_read_b128 v[180:183], v161 offset:3072
	ds_read_b128 v[184:187], v161 offset:4096
	ds_read_b128 v[188:191], v161 offset:5120
	ds_read_b128 v[192:195], v161 offset:6144
	ds_read_b128 v[196:199], v161 offset:7168
	global_load_lds_dwordx4 v[152:153], off
	v_lshl_add_u64 v[152:153], s[20:21], 0, v[132:133]
	s_add_i32 m0, s38, 0xe000
	s_nop 0
	global_load_lds_dwordx4 v[152:153], off
	s_waitcnt lgkmcnt(8)
	s_barrier
	s_waitcnt lgkmcnt(0)
	s_setprio 1
	s_waitcnt lgkmcnt(0)
	v_mfma_f32_16x16x32_bf16 v[124:127], v[140:143], v[168:171], v[124:127]
	v_mfma_f32_16x16x32_bf16 v[120:123], v[148:151], v[168:171], v[120:123]
	v_mfma_f32_16x16x32_bf16 v[108:111], v[140:143], v[176:179], v[108:111]
	v_mfma_f32_16x16x32_bf16 v[104:107], v[148:151], v[176:179], v[104:107]
	v_mfma_f32_16x16x32_bf16 v[92:95], v[140:143], v[184:187], v[92:95]
	v_mfma_f32_16x16x32_bf16 v[88:91], v[148:151], v[184:187], v[88:91]
	v_mfma_f32_16x16x32_bf16 v[76:79], v[140:143], v[192:195], v[76:79]
	v_mfma_f32_16x16x32_bf16 v[72:75], v[148:151], v[192:195], v[72:75]
	v_mfma_f32_16x16x32_bf16 v[124:127], v[144:147], v[172:175], v[124:127]
	v_mfma_f32_16x16x32_bf16 v[120:123], v[164:167], v[172:175], v[120:123]
	v_mfma_f32_16x16x32_bf16 v[108:111], v[144:147], v[180:183], v[108:111]
	v_mfma_f32_16x16x32_bf16 v[104:107], v[164:167], v[180:183], v[104:107]
	v_mfma_f32_16x16x32_bf16 v[92:95], v[144:147], v[188:191], v[92:95]
	v_mfma_f32_16x16x32_bf16 v[88:91], v[164:167], v[188:191], v[88:91]
	v_mfma_f32_16x16x32_bf16 v[76:79], v[144:147], v[196:199], v[76:79]
	v_mfma_f32_16x16x32_bf16 v[72:75], v[164:167], v[196:199], v[72:75]
	s_setprio 0
	s_barrier
	s_add_i32 s20, s52, s37
	v_lshl_add_u64 v[152:153], s[30:31], 0, v[128:129]
	s_mov_b32 m0, s20
	ds_read_b128 v[204:207], v162
	ds_read_b128 v[208:211], v162 offset:1024
	ds_read_b128 v[212:215], v162 offset:2048
	ds_read_b128 v[216:219], v162 offset:3072
	global_load_lds_dwordx4 v[152:153], off
	v_lshl_add_u64 v[200:201], s[30:31], 0, v[130:131]
	s_add_i32 m0, s20, 0x2000
	s_nop 0
	global_load_lds_dwordx4 v[200:201], off
	s_barrier
	s_waitcnt lgkmcnt(0)
	s_setprio 1
	s_waitcnt lgkmcnt(0)
	v_mfma_f32_16x16x32_bf16 v[116:119], v[204:207], v[168:171], v[116:119]
	v_mfma_f32_16x16x32_bf16 v[112:115], v[212:215], v[168:171], v[112:115]
	v_mfma_f32_16x16x32_bf16 v[100:103], v[204:207], v[176:179], v[100:103]
	v_mfma_f32_16x16x32_bf16 v[96:99], v[212:215], v[176:179], v[96:99]
	v_mfma_f32_16x16x32_bf16 v[84:87], v[204:207], v[184:187], v[84:87]
	v_mfma_f32_16x16x32_bf16 v[80:83], v[212:215], v[184:187], v[80:83]
	v_mfma_f32_16x16x32_bf16 v[68:71], v[204:207], v[192:195], v[68:71]
	v_mfma_f32_16x16x32_bf16 v[64:67], v[212:215], v[192:195], v[64:67]
	v_mfma_f32_16x16x32_bf16 v[116:119], v[208:211], v[172:175], v[116:119]
	v_mfma_f32_16x16x32_bf16 v[112:115], v[216:219], v[172:175], v[112:115]
	v_mfma_f32_16x16x32_bf16 v[100:103], v[208:211], v[180:183], v[100:103]
	v_mfma_f32_16x16x32_bf16 v[96:99], v[216:219], v[180:183], v[96:99]
	v_mfma_f32_16x16x32_bf16 v[84:87], v[208:211], v[188:191], v[84:87]
	v_mfma_f32_16x16x32_bf16 v[80:83], v[216:219], v[188:191], v[80:83]
	v_mfma_f32_16x16x32_bf16 v[68:71], v[208:211], v[196:199], v[68:71]
	v_mfma_f32_16x16x32_bf16 v[64:67], v[216:219], v[196:199], v[64:67]
	s_setprio 0
	s_mov_b32 m0, s38
	v_lshl_add_u64 v[220:221], s[34:35], 0, v[128:129]
	s_barrier
	ds_read_b128 v[168:171], v161 offset:16384
	ds_read_b128 v[172:175], v161 offset:17408
	ds_read_b128 v[176:179], v161 offset:18432
	ds_read_b128 v[180:183], v161 offset:19456
	ds_read_b128 v[184:187], v161 offset:20480
	ds_read_b128 v[188:191], v161 offset:21504
	ds_read_b128 v[192:195], v161 offset:22528
	ds_read_b128 v[196:199], v161 offset:23552
	global_load_lds_dwordx4 v[220:221], off
	v_lshl_add_u64 v[222:223], s[34:35], 0, v[130:131]
	s_mov_b32 m0, s39
	s_nop 0
	global_load_lds_dwordx4 v[222:223], off
	s_barrier
	s_waitcnt lgkmcnt(0)
	s_setprio 1
	s_waitcnt lgkmcnt(0)
	v_mfma_f32_16x16x32_bf16 v[60:63], v[140:143], v[168:171], v[60:63]
	v_mfma_f32_16x16x32_bf16 v[56:59], v[148:151], v[168:171], v[56:59]
	v_mfma_f32_16x16x32_bf16 v[44:47], v[140:143], v[176:179], v[44:47]
	v_mfma_f32_16x16x32_bf16 v[40:43], v[148:151], v[176:179], v[40:43]
	v_mfma_f32_16x16x32_bf16 v[28:31], v[140:143], v[184:187], v[28:31]
	v_mfma_f32_16x16x32_bf16 v[24:27], v[148:151], v[184:187], v[24:27]
	v_mfma_f32_16x16x32_bf16 v[16:19], v[140:143], v[192:195], v[16:19]
	v_mfma_f32_16x16x32_bf16 v[8:11], v[148:151], v[192:195], v[8:11]
	v_mfma_f32_16x16x32_bf16 v[60:63], v[144:147], v[172:175], v[60:63]
	v_mfma_f32_16x16x32_bf16 v[56:59], v[164:167], v[172:175], v[56:59]
	v_mfma_f32_16x16x32_bf16 v[44:47], v[144:147], v[180:183], v[44:47]
	v_mfma_f32_16x16x32_bf16 v[40:43], v[164:167], v[180:183], v[40:43]
	v_mfma_f32_16x16x32_bf16 v[28:31], v[144:147], v[188:191], v[28:31]
	v_mfma_f32_16x16x32_bf16 v[24:27], v[164:167], v[188:191], v[24:27]
	v_mfma_f32_16x16x32_bf16 v[16:19], v[144:147], v[196:199], v[16:19]
	v_mfma_f32_16x16x32_bf16 v[8:11], v[164:167], v[196:199], v[8:11]
	s_setprio 0
	s_barrier
; #define G_STAGE(bufoff, gbase, voff) do { _Pragma("unroll") for (int _i = 0; _i < 2; ++_i) \
;         __builtin_amdgcn_global_load_lds((const unsigned*)((const char*)(gbase) + (voff)[_i]), (LAS unsigned*)(lds + (bufoff) + ldsw + _i * 8192), 16, 0, 0); } while (0)
; #define G_LDA(dst, b, h) do { _Pragma("unroll") for (int m = 0; m < 4; ++m) _Pragma("unroll") for (int k = 0; k < 2; ++k) dst[m][k] = *(const LAS bf16x8*)(lds + G_SA(b, h) + aoff + m * 2048 + k * 1024); } while (0)
; #define G_LDB(dst, b, h) do { _Pragma("unroll") for (int n = 0; n < 2; ++n) _Pragma("unroll") for (int k = 0; k < 2; ++k) dst[n][k] = *(const LAS bf16x8*)(lds + G_SB(b, h) + boff + n * 2048 + k * 1024); } while (0)
; #define G_MMA(ai, bj, At, Bt_) do { __builtin_amdgcn_s_setprio(1); _Pragma("unroll") for (int m = 0; m < 4; ++m) _Pragma("unroll") for (int n = 0; n < 2; ++n) _Pragma("unroll") for (int k = 0; k < 2; ++k) \
;         acc[ai][bj][m][n] = __builtin_amdgcn_mfma_f32_16x16x32_bf16(Bt_[n][k], At[m][k], acc[ai][bj][m][n], 0, 0, 0); __builtin_amdgcn_s_setprio(0); } while (0)
; #define G_WAIT_V(n) asm volatile("s_waitcnt vmcnt(" #n ")" ::: "memory")
; #define G_WAIT_L(n) asm volatile("s_waitcnt lgkmcnt(" #n ")" ::: "memory")
; #define G_BAR __builtin_amdgcn_s_barrier()
; #define G_SCHED __builtin_amdgcn_sched_barrier(0)
; template <class Epi, bool PERMROWS = false>
; DI void gemm_phase(LAS unsigned char* lds, const bf16_t* A, int lda, const bf16_t* Bt, int K, const Sched& S, const Epi& E) {
;     ...
;             G_WAIT_V(6); G_BAR; G_MMA(1, 1, At, B1); G_BAR;
;             G_LDB(B0, 1, 0); G_SCHED; G_LDA(At, 1, 0); G_STAGE(G_SA(0, 1), a2 + hstepA, voffA);
;             G_WAIT_L(8); G_BAR; G_WAIT_L(0); G_MMA(0, 0, At, B0); G_BAR; G_SCHED;
;             G_LDB(B1, 1, 1); G_STAGE(G_SB(1, 0), b3, voffB);
;             G_BAR; G_WAIT_L(0); G_MMA(0, 1, At, B1); G_BAR;
;             G_LDA(At, 1, 1); G_STAGE(G_SA(1, 0), a3, voffA);
;             G_BAR; G_WAIT_L(0); G_MMA(1, 0, At, B0); G_BAR; G_SCHED;
	s_add_u32 s20, s30, 0x160000
	s_addc_u32 s21, s31, 0
	s_add_i32 s62, s53, s37
	v_lshl_add_u64 v[140:141], s[20:21], 0, v[128:129]
	s_mov_b32 m0, s62
	s_nop 0
	global_load_lds_dwordx4 v[140:141], off
	v_lshl_add_u64 v[140:141], s[20:21], 0, v[130:131]
	s_add_i32 m0, s62, 0x2000
	s_nop 0
	global_load_lds_dwordx4 v[140:141], off
	s_waitcnt vmcnt(6)
	s_barrier
	s_setprio 1
	v_mfma_f32_16x16x32_bf16 v[52:55], v[204:207], v[168:171], v[52:55]
	v_mfma_f32_16x16x32_bf16 v[48:51], v[212:215], v[168:171], v[48:51]
	v_mfma_f32_16x16x32_bf16 v[36:39], v[204:207], v[176:179], v[36:39]
	v_mfma_f32_16x16x32_bf16 v[32:35], v[212:215], v[176:179], v[32:35]
	v_mfma_f32_16x16x32_bf16 v[20:23], v[204:207], v[184:187], v[20:23]
	v_mfma_f32_16x16x32_bf16 v[12:15], v[212:215], v[184:187], v[12:15]
	v_mfma_f32_16x16x32_bf16 v[4:7], v[204:207], v[192:195], v[4:7]
	v_mfma_f32_16x16x32_bf16 v[0:3], v[212:215], v[192:195], v[0:3]
	v_mfma_f32_16x16x32_bf16 v[52:55], v[208:211], v[172:175], v[52:55]
	v_mfma_f32_16x16x32_bf16 v[48:51], v[216:219], v[172:175], v[48:51]
	v_mfma_f32_16x16x32_bf16 v[36:39], v[208:211], v[180:183], v[36:39]
	v_mfma_f32_16x16x32_bf16 v[32:35], v[216:219], v[180:183], v[32:35]
	v_mfma_f32_16x16x32_bf16 v[20:23], v[208:211], v[188:191], v[20:23]
	v_mfma_f32_16x16x32_bf16 v[12:15], v[216:219], v[188:191], v[12:15]
	v_mfma_f32_16x16x32_bf16 v[4:7], v[208:211], v[196:199], v[4:7]
	v_mfma_f32_16x16x32_bf16 v[0:3], v[216:219], v[196:199], v[0:3]
	s_setprio 0
	s_add_i32 s62, 0, 0x18000
	v_add_u32_e32 v163, s62, v155
	s_barrier
	ds_read_b128 v[140:143], v163
	ds_read_b128 v[144:147], v163 offset:1024
	ds_read_b128 v[148:151], v163 offset:2048
	ds_read_b128 v[164:167], v163 offset:3072
	s_add_u32 s20, s34, 0x160000
	s_addc_u32 s21, s35, 0
	s_mov_b32 m0, s40
	v_lshl_add_u64 v[204:205], s[20:21], 0, v[128:129]
	ds_read_b128 v[168:171], v161 offset:32768
	ds_read_b128 v[172:175], v161 offset:33792
	ds_read_b128 v[176:179], v161 offset:34816
	ds_read_b128 v[180:183], v161 offset:35840
	ds_read_b128 v[184:187], v161 offset:36864
	ds_read_b128 v[188:191], v161 offset:37888
	ds_read_b128 v[192:195], v161 offset:38912
	ds_read_b128 v[196:199], v161 offset:39936
	global_load_lds_dwordx4 v[204:205], off
	v_lshl_add_u64 v[204:205], s[20:21], 0, v[130:131]
	s_mov_b32 m0, s41
	s_nop 0
	global_load_lds_dwordx4 v[204:205], off
	s_waitcnt lgkmcnt(8)
	s_barrier
	s_waitcnt lgkmcnt(0)
	s_setprio 1
	s_waitcnt lgkmcnt(0)
	v_mfma_f32_16x16x32_bf16 v[124:127], v[140:143], v[168:171], v[124:127]
	v_mfma_f32_16x16x32_bf16 v[120:123], v[148:151], v[168:171], v[120:123]
	v_mfma_f32_16x16x32_bf16 v[108:111], v[140:143], v[176:179], v[108:111]
	v_mfma_f32_16x16x32_bf16 v[104:107], v[148:151], v[176:179], v[104:107]
	v_mfma_f32_16x16x32_bf16 v[92:95], v[140:143], v[184:187], v[92:95]
	v_mfma_f32_16x16x32_bf16 v[88:91], v[148:151], v[184:187], v[88:91]
	v_mfma_f32_16x16x32_bf16 v[76:79], v[140:143], v[192:195], v[76:79]
	v_mfma_f32_16x16x32_bf16 v[72:75], v[148:151], v[192:195], v[72:75]
	v_mfma_f32_16x16x32_bf16 v[124:127], v[144:147], v[172:175], v[124:127]
	v_mfma_f32_16x16x32_bf16 v[120:123], v[164:167], v[172:175], v[120:123]
	v_mfma_f32_16x16x32_bf16 v[108:111], v[144:147], v[180:183], v[108:111]
	v_mfma_f32_16x16x32_bf16 v[104:107], v[164:167], v[180:183], v[104:107]
	v_mfma_f32_16x16x32_bf16 v[92:95], v[144:147], v[188:191], v[92:95]
	v_mfma_f32_16x16x32_bf16 v[88:91], v[164:167], v[188:191], v[88:91]
	v_mfma_f32_16x16x32_bf16 v[76:79], v[144:147], v[196:199], v[76:79]
	v_mfma_f32_16x16x32_bf16 v[72:75], v[164:167], v[196:199], v[72:75]
	s_setprio 0
	s_barrier
	s_add_i32 s34, 0, 0x1c000
	s_add_i32 s20, s62, s37
	v_add_u32_e32 v163, s34, v155
	v_lshl_add_u64 v[152:153], v[152:153], 0, s[10:11]
	s_mov_b32 m0, s20
	ds_read_b128 v[204:207], v163
	ds_read_b128 v[208:211], v163 offset:1024
	ds_read_b128 v[212:215], v163 offset:2048
	ds_read_b128 v[216:219], v163 offset:3072
	global_load_lds_dwordx4 v[152:153], off
	v_lshl_add_u64 v[152:153], v[200:201], 0, s[10:11]
	s_add_i32 m0, s20, 0x2000
	s_nop 0
	global_load_lds_dwordx4 v[152:153], off
	s_barrier
	s_waitcnt lgkmcnt(0)
	s_setprio 1
	s_waitcnt lgkmcnt(0)
	v_mfma_f32_16x16x32_bf16 v[116:119], v[204:207], v[168:171], v[116:119]
	v_mfma_f32_16x16x32_bf16 v[112:115], v[212:215], v[168:171], v[112:115]
	v_mfma_f32_16x16x32_bf16 v[100:103], v[204:207], v[176:179], v[100:103]
	v_mfma_f32_16x16x32_bf16 v[96:99], v[212:215], v[176:179], v[96:99]
	v_mfma_f32_16x16x32_bf16 v[84:87], v[204:207], v[184:187], v[84:87]
	v_mfma_f32_16x16x32_bf16 v[80:83], v[212:215], v[184:187], v[80:83]
	v_mfma_f32_16x16x32_bf16 v[68:71], v[204:207], v[192:195], v[68:71]
	v_mfma_f32_16x16x32_bf16 v[64:67], v[212:215], v[192:195], v[64:67]
	v_mfma_f32_16x16x32_bf16 v[116:119], v[208:211], v[172:175], v[116:119]
	v_mfma_f32_16x16x32_bf16 v[112:115], v[216:219], v[172:175], v[112:115]
	v_mfma_f32_16x16x32_bf16 v[100:103], v[208:211], v[180:183], v[100:103]
	v_mfma_f32_16x16x32_bf16 v[96:99], v[216:219], v[180:183], v[96:99]
	v_mfma_f32_16x16x32_bf16 v[84:87], v[208:211], v[188:191], v[84:87]
	v_mfma_f32_16x16x32_bf16 v[80:83], v[216:219], v[188:191], v[80:83]
	v_mfma_f32_16x16x32_bf16 v[68:71], v[208:211], v[196:199], v[68:71]
	v_mfma_f32_16x16x32_bf16 v[64:67], v[216:219], v[196:199], v[64:67]
	s_setprio 0
	s_mov_b32 m0, s55
	v_lshl_add_u64 v[152:153], v[220:221], 0, s[10:11]
	s_barrier
	ds_read_b128 v[168:171], v161 offset:49152
	ds_read_b128 v[172:175], v161 offset:50176
	ds_read_b128 v[176:179], v161 offset:51200
	ds_read_b128 v[180:183], v161 offset:52224
	ds_read_b128 v[184:187], v161 offset:53248
	ds_read_b128 v[188:191], v161 offset:54272
	ds_read_b128 v[192:195], v161 offset:55296
	ds_read_b128 v[196:199], v161 offset:56320
	global_load_lds_dwordx4 v[152:153], off
	v_lshl_add_u64 v[152:153], v[222:223], 0, s[10:11]
	s_mov_b32 m0, s56
	s_nop 0
	global_load_lds_dwordx4 v[152:153], off
	s_barrier
; #define G_STAGE(bufoff, gbase, voff) do { _Pragma("unroll") for (int _i = 0; _i < 2; ++_i) \
;         __builtin_amdgcn_global_load_lds((const unsigned*)((const char*)(gbase) + (voff)[_i]), (LAS unsigned*)(lds + (bufoff) + ldsw + _i * 8192), 16, 0, 0); } while (0)
; #define G_MMA(ai, bj, At, Bt_) do { __builtin_amdgcn_s_setprio(1); _Pragma("unroll") for (int m = 0; m < 4; ++m) _Pragma("unroll") for (int n = 0; n < 2; ++n) _Pragma("unroll") for (int k = 0; k < 2; ++k) \
;         acc[ai][bj][m][n] = __builtin_amdgcn_mfma_f32_16x16x32_bf16(Bt_[n][k], At[m][k], acc[ai][bj][m][n], 0, 0, 0); __builtin_amdgcn_s_setprio(0); } while (0)
; #define G_WAIT_V(n) asm volatile("s_waitcnt vmcnt(" #n ")" ::: "memory")
; #define G_WAIT_L(n) asm volatile("s_waitcnt lgkmcnt(" #n ")" ::: "memory")
; #define G_BAR __builtin_amdgcn_s_barrier()
; #define G_SCHED __builtin_amdgcn_sched_barrier(0)
; template <class Epi, bool PERMROWS = false>
; DI void gemm_phase(LAS unsigned char* lds, const bf16_t* A, int lda, const bf16_t* Bt, int K, const Sched& S, const Epi& E) {
;     ...
;             G_BAR; G_WAIT_L(0); G_MMA(1, 0, At, B0); G_BAR; G_SCHED;
;             G_STAGE(G_SB(1, 1), b3 + hstepB, voffB);
;             G_WAIT_V(6); G_BAR; G_MMA(1, 1, At, B1); G_BAR;
;         }
;         E(acc, cur, wr, wc, fr, fq);
;     DI void operator()(const f32x4 (&acc)[2][2][4][2], const Unit& u, int wr, int wc, int fr, int fq) const {
;     ...
;         const float* g = gate + (size_t)s * 12288;
;         const float2* RS = (const float2*)(ws + WS_RSTAT);
; #pragma unroll
;         for (int ai = 0; ai < 2; ++ai)
; #pragma unroll
;             for (int m = 0; m < 4; ++m) {
;                 const int row = u.pm * BM + ai * HALF + wr * 64 + m * 16 + fr;
;                 float mu = 0.f, rs = 1.f;
;                 if (pg) { const float2 st = RS[row]; mu = st.x; rs = st.y; }
; #pragma unroll
;                 for (int bj = 0; bj < 2; ++bj)
; #pragma unroll
;                     for (int n = 0; n < 2; ++n) {
;                         const int col = u.pn * BM + bj * HALF + wc * 32 + n * 16 + 4 * fq;
;                         float* xp = X + (size_t)row * DM + col;
;                         f32x4 x4 = *(const f32x4*)xp; const f32x4 g4 = *(const f32x4*)(g + col);
;                         if (pg) x4 = (x4 - mu) * rs * *(const f32x4*)(pg + col) + *(const f32x4*)(pb + col);
	s_waitcnt lgkmcnt(0)
	s_setprio 1
	s_waitcnt lgkmcnt(0)
	v_mfma_f32_16x16x32_bf16 v[60:63], v[140:143], v[168:171], v[60:63]
	v_mfma_f32_16x16x32_bf16 v[56:59], v[148:151], v[168:171], v[56:59]
	v_mfma_f32_16x16x32_bf16 v[44:47], v[140:143], v[176:179], v[44:47]
	v_mfma_f32_16x16x32_bf16 v[40:43], v[148:151], v[176:179], v[40:43]
	v_mfma_f32_16x16x32_bf16 v[28:31], v[140:143], v[184:187], v[28:31]
	v_mfma_f32_16x16x32_bf16 v[24:27], v[148:151], v[184:187], v[24:27]
	v_mfma_f32_16x16x32_bf16 v[16:19], v[140:143], v[192:195], v[16:19]
	v_mfma_f32_16x16x32_bf16 v[8:11], v[148:151], v[192:195], v[8:11]
	v_mfma_f32_16x16x32_bf16 v[60:63], v[144:147], v[172:175], v[60:63]
	v_mfma_f32_16x16x32_bf16 v[56:59], v[164:167], v[172:175], v[56:59]
	v_mfma_f32_16x16x32_bf16 v[44:47], v[144:147], v[180:183], v[44:47]
	v_mfma_f32_16x16x32_bf16 v[40:43], v[164:167], v[180:183], v[40:43]
	v_mfma_f32_16x16x32_bf16 v[28:31], v[144:147], v[188:191], v[28:31]
	v_mfma_f32_16x16x32_bf16 v[24:27], v[164:167], v[188:191], v[24:27]
	v_mfma_f32_16x16x32_bf16 v[16:19], v[144:147], v[196:199], v[16:19]
	v_mfma_f32_16x16x32_bf16 v[8:11], v[164:167], v[196:199], v[8:11]
	s_setprio 0
	s_barrier
	s_add_u32 s20, s30, 0x160080
	s_addc_u32 s21, s31, 0
	s_add_i32 s30, s34, s37
	v_lshl_add_u64 v[140:141], s[20:21], 0, v[128:129]
	s_mov_b32 m0, s30
	s_nop 0
	global_load_lds_dwordx4 v[140:141], off
	v_lshl_add_u64 v[140:141], s[20:21], 0, v[130:131]
	s_add_i32 m0, s30, 0x2000
	s_nop 0
	global_load_lds_dwordx4 v[140:141], off
	s_waitcnt vmcnt(6)
	s_barrier
	s_setprio 1
	v_mfma_f32_16x16x32_bf16 v[52:55], v[204:207], v[168:171], v[52:55]
	v_mfma_f32_16x16x32_bf16 v[48:51], v[212:215], v[168:171], v[48:51]
	v_mfma_f32_16x16x32_bf16 v[36:39], v[204:207], v[176:179], v[36:39]
	v_mfma_f32_16x16x32_bf16 v[32:35], v[212:215], v[176:179], v[32:35]
	v_mfma_f32_16x16x32_bf16 v[20:23], v[204:207], v[184:187], v[20:23]
	v_mfma_f32_16x16x32_bf16 v[12:15], v[212:215], v[184:187], v[12:15]
	v_mfma_f32_16x16x32_bf16 v[4:7], v[204:207], v[192:195], v[4:7]
	v_mfma_f32_16x16x32_bf16 v[0:3], v[212:215], v[192:195], v[0:3]
	v_mfma_f32_16x16x32_bf16 v[52:55], v[208:211], v[172:175], v[52:55]
	v_mfma_f32_16x16x32_bf16 v[48:51], v[216:219], v[172:175], v[48:51]
	v_mfma_f32_16x16x32_bf16 v[36:39], v[208:211], v[180:183], v[36:39]
	v_mfma_f32_16x16x32_bf16 v[32:35], v[216:219], v[180:183], v[32:35]
	v_mfma_f32_16x16x32_bf16 v[20:23], v[208:211], v[188:191], v[20:23]
	v_mfma_f32_16x16x32_bf16 v[12:15], v[216:219], v[188:191], v[12:15]
	v_mfma_f32_16x16x32_bf16 v[4:7], v[208:211], v[196:199], v[4:7]
	v_mfma_f32_16x16x32_bf16 v[0:3], v[216:219], v[196:199], v[0:3]
	s_setprio 0
	s_add_i32 s29, s29, 2
	s_add_u32 s61, s61, 0x100
	s_addc_u32 s28, s28, 0
	s_cmpk_gt_u32 s29, 0x55
	s_mov_b64 s[20:21], s[22:23]
	s_barrier
	s_cbranch_scc0 .LBB0_3113
	v_and_b32_e32 v175, 15, v202
	v_bfe_u32 v176, v202, 8, 1
	v_lshl_add_u32 v175, v176, 6, v175
	v_lshlrev_b32_e32 v166, 3, v175
	v_bfe_u32 v176, v202, 6, 2
	v_lshlrev_b32_e32 v163, 7, v176
	v_bfe_u32 v176, v202, 4, 2
	v_lshl_add_u32 v163, v176, 4, v163
	s_lshl_b32 s29, s60, 10
	v_add_u32_e32 v163, s29, v163
	v_lshl_add_u32 v167, v175, 13, v163
	v_add_u32_e32 v168, 0x20000, v167
	v_add_u32_e32 v169, 0x40000, v167
	v_add_u32_e32 v170, 0x60000, v167
	v_add_u32_e32 v171, 0x100000, v167
	v_add_u32_e32 v172, 0x120000, v167
	v_add_u32_e32 v173, 0x140000, v167
	v_add_u32_e32 v174, 0x160000, v167
	s_mov_b32 s89, 0x3fb504f3
	s_mul_i32 s29, s59, 57
	s_lshr_b32 s29, s29, 9
	s_mul_i32 s32, s29, 9
	s_cmp_lg_u32 s32, s59
	s_cselect_b32 s28, s29, 4
	s_mul_i32 s28, s28, 0xc000
	s_add_u32 s74, s50, 0x4e000
	s_addc_u32 s75, s51, 0
	s_add_u32 s74, s74, s28
	s_addc_u32 s75, s75, 0
	global_load_dwordx4 v[220:223], v163, s[74:75] offset:0
	global_load_dwordx4 v[224:227], v163, s[74:75] offset:64
	global_load_dwordx4 v[228:231], v163, s[74:75] offset:512
	global_load_dwordx4 v[232:235], v163, s[74:75] offset:576
	s_add_u32 s74, s64, 0x2000
	s_addc_u32 s75, s65, 0
	global_load_dwordx4 v[204:207], v163, s[74:75] offset:0
	global_load_dwordx4 v[208:211], v163, s[74:75] offset:64
	global_load_dwordx4 v[212:215], v163, s[74:75] offset:512
	global_load_dwordx4 v[216:219], v163, s[74:75] offset:576
	s_add_u32 s74, s66, 0x2000
	s_addc_u32 s75, s67, 0
	global_load_dwordx4 v[236:239], v163, s[74:75] offset:0
	global_load_dwordx4 v[240:243], v163, s[74:75] offset:64
	global_load_dwordx4 v[244:247], v163, s[74:75] offset:512
	global_load_dwordx4 v[248:251], v163, s[74:75] offset:576
	s_lshl_b32 s29, s59, 11
	s_add_u32 s74, s50, 0x260a0000
	s_addc_u32 s75, s51, 0
	s_add_u32 s74, s74, s29
	s_addc_u32 s75, s75, 0
	global_load_dwordx2 v[140:141], v166, s[74:75] offset:0
	global_load_dwordx2 v[142:143], v166, s[74:75] offset:128
	global_load_dwordx2 v[144:145], v166, s[74:75] offset:256
	global_load_dwordx2 v[146:147], v166, s[74:75] offset:384
	global_load_dwordx2 v[148:149], v166, s[74:75] offset:1024
	global_load_dwordx2 v[150:151], v166, s[74:75] offset:1152
	global_load_dwordx2 v[152:153], v166, s[74:75] offset:1280
	global_load_dwordx2 v[164:165], v166, s[74:75] offset:1408
	s_lshl_b32 s29, s59, 21
	s_add_u32 s72, s50, 0xcba0000
	s_addc_u32 s73, s51, 0
	s_add_u32 s72, s72, s29
	s_addc_u32 s73, s73, 0
	s_waitcnt vmcnt(0)
;     DI void operator()(const f32x4 (&acc)[2][2][4][2], const Unit& u, int wr, int wc, int fr, int fq) const {
;     ...
;                         float* xp = X + (size_t)row * DM + col;
;                         f32x4 x4 = *(const f32x4*)xp; const f32x4 g4 = *(const f32x4*)(g + col);
;                         if (pg) x4 = (x4 - mu) * rs * *(const f32x4*)(pg + col) + *(const f32x4*)(pb + col);
;                         *(f32x4*)xp = x4 * ALPHA + g4 * acc[ai][bj][m][n];
	v_mul_f32_e32 v204, s89, v204
	v_mul_f32_e32 v236, s89, v236
	v_mul_f32_e32 v205, s89, v205
	v_mul_f32_e32 v237, s89, v237
	v_mul_f32_e32 v206, s89, v206
	v_mul_f32_e32 v238, s89, v238
	v_mul_f32_e32 v207, s89, v207
	v_mul_f32_e32 v239, s89, v239
	v_mul_f32_e32 v208, s89, v208
	v_mul_f32_e32 v240, s89, v240
	v_mul_f32_e32 v209, s89, v209
	v_mul_f32_e32 v241, s89, v241
	v_mul_f32_e32 v210, s89, v210
	v_mul_f32_e32 v242, s89, v242
	v_mul_f32_e32 v211, s89, v211
	v_mul_f32_e32 v243, s89, v243
	v_mul_f32_e32 v212, s89, v212
	v_mul_f32_e32 v244, s89, v244
	v_mul_f32_e32 v213, s89, v213
	v_mul_f32_e32 v245, s89, v245
	v_mul_f32_e32 v214, s89, v214
	v_mul_f32_e32 v246, s89, v246
	v_mul_f32_e32 v215, s89, v215
	v_mul_f32_e32 v247, s89, v247
	v_mul_f32_e32 v216, s89, v216
	v_mul_f32_e32 v248, s89, v248
	v_mul_f32_e32 v217, s89, v217
	v_mul_f32_e32 v249, s89, v249
	v_mul_f32_e32 v218, s89, v218
	v_mul_f32_e32 v250, s89, v250
	v_mul_f32_e32 v219, s89, v219
	v_mul_f32_e32 v251, s89, v251
	v_fma_f32 v124, v220, v124, v236
	v_fma_f32 v125, v221, v125, v237
	v_fma_f32 v126, v222, v126, v238
	v_fma_f32 v127, v223, v127, v239
	v_fma_f32 v120, v224, v120, v240
	v_fma_f32 v121, v225, v121, v241
	v_fma_f32 v122, v226, v122, v242
	v_fma_f32 v123, v227, v123, v243
	v_fma_f32 v116, v228, v116, v244
	v_fma_f32 v117, v229, v117, v245
	v_fma_f32 v118, v230, v118, v246
	v_fma_f32 v119, v231, v119, v247
	v_fma_f32 v112, v232, v112, v248
	v_fma_f32 v113, v233, v113, v249
	v_fma_f32 v114, v234, v114, v250
	v_fma_f32 v115, v235, v115, v251
	v_fma_f32 v108, v220, v108, v236
	v_fma_f32 v109, v221, v109, v237
	v_fma_f32 v110, v222, v110, v238
	v_fma_f32 v111, v223, v111, v239
	v_fma_f32 v104, v224, v104, v240
	v_fma_f32 v105, v225, v105, v241
	v_fma_f32 v106, v226, v106, v242
	v_fma_f32 v107, v227, v107, v243
	v_fma_f32 v100, v228, v100, v244
	v_fma_f32 v101, v229, v101, v245
	v_fma_f32 v102, v230, v102, v246
	v_fma_f32 v103, v231, v103, v247
	v_fma_f32 v96, v232, v96, v248
	v_fma_f32 v97, v233, v97, v249
	v_fma_f32 v98, v234, v98, v250
	v_fma_f32 v99, v235, v99, v251
	v_fma_f32 v92, v220, v92, v236
	v_fma_f32 v93, v221, v93, v237
	v_fma_f32 v94, v222, v94, v238
	v_fma_f32 v95, v223, v95, v239
	v_fma_f32 v88, v224, v88, v240
	v_fma_f32 v89, v225, v89, v241
	v_fma_f32 v90, v226, v90, v242
	v_fma_f32 v91, v227, v91, v243
	v_fma_f32 v84, v228, v84, v244
	v_fma_f32 v85, v229, v85, v245
	v_fma_f32 v86, v230, v86, v246
	v_fma_f32 v87, v231, v87, v247
	v_fma_f32 v80, v232, v80, v248
	v_fma_f32 v81, v233, v81, v249
	v_fma_f32 v82, v234, v82, v250
	v_fma_f32 v83, v235, v83, v251
	v_fma_f32 v76, v220, v76, v236
	v_fma_f32 v77, v221, v77, v237
	v_fma_f32 v78, v222, v78, v238
	v_fma_f32 v79, v223, v79, v239
	v_fma_f32 v72, v224, v72, v240
	v_fma_f32 v73, v225, v73, v241
	v_fma_f32 v74, v226, v74, v242
	v_fma_f32 v75, v227, v75, v243
	v_fma_f32 v68, v228, v68, v244
	v_fma_f32 v69, v229, v69, v245
	v_fma_f32 v70, v230, v70, v246
	v_fma_f32 v71, v231, v71, v247
	v_fma_f32 v64, v232, v64, v248
	v_fma_f32 v65, v233, v65, v249
	v_fma_f32 v66, v234, v66, v250
	v_fma_f32 v67, v235, v67, v251
	v_fma_f32 v60, v220, v60, v236
	v_fma_f32 v61, v221, v61, v237
	v_fma_f32 v62, v222, v62, v238
	v_fma_f32 v63, v223, v63, v239
	v_fma_f32 v56, v224, v56, v240
	v_fma_f32 v57, v225, v57, v241
	v_fma_f32 v58, v226, v58, v242
	v_fma_f32 v59, v227, v59, v243
	v_fma_f32 v52, v228, v52, v244
	v_fma_f32 v53, v229, v53, v245
	v_fma_f32 v54, v230, v54, v246
	v_fma_f32 v55, v231, v55, v247
	v_fma_f32 v48, v232, v48, v248
	v_fma_f32 v49, v233, v49, v249
	v_fma_f32 v50, v234, v50, v250
	v_fma_f32 v51, v235, v51, v251
	v_fma_f32 v44, v220, v44, v236
	v_fma_f32 v45, v221, v45, v237
	v_fma_f32 v46, v222, v46, v238
	v_fma_f32 v47, v223, v47, v239
	v_fma_f32 v40, v224, v40, v240
	v_fma_f32 v41, v225, v41, v241
	v_fma_f32 v42, v226, v42, v242
	v_fma_f32 v43, v227, v43, v243
	v_fma_f32 v36, v228, v36, v244
	v_fma_f32 v37, v229, v37, v245
	v_fma_f32 v38, v230, v38, v246
	v_fma_f32 v39, v231, v39, v247
	v_fma_f32 v32, v232, v32, v248
	v_fma_f32 v33, v233, v33, v249
	v_fma_f32 v34, v234, v34, v250
	v_fma_f32 v35, v235, v35, v251
	v_fma_f32 v28, v220, v28, v236
	v_fma_f32 v29, v221, v29, v237
	v_fma_f32 v30, v222, v30, v238
	v_fma_f32 v31, v223, v31, v239
	v_fma_f32 v24, v224, v24, v240
	v_fma_f32 v25, v225, v25, v241
	v_fma_f32 v26, v226, v26, v242
	v_fma_f32 v27, v227, v27, v243
	v_fma_f32 v20, v228, v20, v244
	v_fma_f32 v21, v229, v21, v245
	v_fma_f32 v22, v230, v22, v246
	v_fma_f32 v23, v231, v23, v247
	v_fma_f32 v12, v232, v12, v248
	v_fma_f32 v13, v233, v13, v249
	v_fma_f32 v14, v234, v14, v250
	v_fma_f32 v15, v235, v15, v251
	v_fma_f32 v16, v220, v16, v236
	v_fma_f32 v17, v221, v17, v237
	v_fma_f32 v18, v222, v18, v238
	v_fma_f32 v19, v223, v19, v239
	v_fma_f32 v8, v224, v8, v240
	v_fma_f32 v9, v225, v9, v241
	v_fma_f32 v10, v226, v10, v242
	v_fma_f32 v11, v227, v11, v243
	v_fma_f32 v4, v228, v4, v244
	v_fma_f32 v5, v229, v5, v245
	v_fma_f32 v6, v230, v6, v246
	v_fma_f32 v7, v231, v7, v247
	v_fma_f32 v0, v232, v0, v248
	v_fma_f32 v1, v233, v1, v249
	v_fma_f32 v2, v234, v2, v250
	v_fma_f32 v3, v235, v3, v251
	global_load_dwordx4 v[220:223], v167, s[72:73] offset:0
	global_load_dwordx4 v[224:227], v167, s[72:73] offset:64
	global_load_dwordx4 v[228:231], v167, s[72:73] offset:512
	global_load_dwordx4 v[232:235], v167, s[72:73] offset:576
	global_load_dwordx4 v[236:239], v168, s[72:73] offset:0
	global_load_dwordx4 v[240:243], v168, s[72:73] offset:64
	global_load_dwordx4 v[244:247], v168, s[72:73] offset:512
	global_load_dwordx4 v[248:251], v168, s[72:73] offset:576
	s_waitcnt vmcnt(0)
;     DI void operator()(const f32x4 (&acc)[2][2][4][2], const Unit& u, int wr, int wc, int fr, int fq) const {
;     ...
;                 const int row = u.pm * BM + ai * HALF + wr * 64 + m * 16 + fr;
;                 float mu = 0.f, rs = 1.f;
;                 if (pg) { const float2 st = RS[row]; mu = st.x; rs = st.y; }
; #pragma unroll
;                 for (int bj = 0; bj < 2; ++bj)
; #pragma unroll
;                     for (int n = 0; n < 2; ++n) {
;                         const int col = u.pn * BM + bj * HALF + wc * 32 + n * 16 + 4 * fq;
;                         float* xp = X + (size_t)row * DM + col;
;                         f32x4 x4 = *(const f32x4*)xp; const f32x4 g4 = *(const f32x4*)(g + col);
;                         if (pg) x4 = (x4 - mu) * rs * *(const f32x4*)(pg + col) + *(const f32x4*)(pb + col);
;                         *(f32x4*)xp = x4 * ALPHA + g4 * acc[ai][bj][m][n];
;                     }
	v_sub_f32_e32 v220, v220, v140
	v_mul_f32_e32 v220, v220, v141
	v_fma_f32 v220, v220, v204, v124
	v_sub_f32_e32 v221, v221, v140
	v_mul_f32_e32 v221, v221, v141
	v_fma_f32 v221, v221, v205, v125
	v_sub_f32_e32 v222, v222, v140
	v_mul_f32_e32 v222, v222, v141
	v_fma_f32 v222, v222, v206, v126
	v_sub_f32_e32 v223, v223, v140
	v_mul_f32_e32 v223, v223, v141
	v_fma_f32 v223, v223, v207, v127
	v_sub_f32_e32 v224, v224, v140
	v_mul_f32_e32 v224, v224, v141
	v_fma_f32 v224, v224, v208, v120
	v_sub_f32_e32 v225, v225, v140
	v_mul_f32_e32 v225, v225, v141
	v_fma_f32 v225, v225, v209, v121
	v_sub_f32_e32 v226, v226, v140
	v_mul_f32_e32 v226, v226, v141
	v_fma_f32 v226, v226, v210, v122
	v_sub_f32_e32 v227, v227, v140
	v_mul_f32_e32 v227, v227, v141
	v_fma_f32 v227, v227, v211, v123
	v_sub_f32_e32 v228, v228, v140
	v_mul_f32_e32 v228, v228, v141
	v_fma_f32 v228, v228, v212, v116
	v_sub_f32_e32 v229, v229, v140
	v_mul_f32_e32 v229, v229, v141
	v_fma_f32 v229, v229, v213, v117
	v_sub_f32_e32 v230, v230, v140
	v_mul_f32_e32 v230, v230, v141
	v_fma_f32 v230, v230, v214, v118
	v_sub_f32_e32 v231, v231, v140
	v_mul_f32_e32 v231, v231, v141
	v_fma_f32 v231, v231, v215, v119
	v_sub_f32_e32 v232, v232, v140
	v_mul_f32_e32 v232, v232, v141
	v_fma_f32 v232, v232, v216, v112
	v_sub_f32_e32 v233, v233, v140
	v_mul_f32_e32 v233, v233, v141
	v_fma_f32 v233, v233, v217, v113
	v_sub_f32_e32 v234, v234, v140
	v_mul_f32_e32 v234, v234, v141
	v_fma_f32 v234, v234, v218, v114
	v_sub_f32_e32 v235, v235, v140
	v_mul_f32_e32 v235, v235, v141
	v_fma_f32 v235, v235, v219, v115
	v_sub_f32_e32 v236, v236, v142
	v_mul_f32_e32 v236, v236, v143
	v_fma_f32 v236, v236, v204, v108
	v_sub_f32_e32 v237, v237, v142
	v_mul_f32_e32 v237, v237, v143
	v_fma_f32 v237, v237, v205, v109
	v_sub_f32_e32 v238, v238, v142
	v_mul_f32_e32 v238, v238, v143
	v_fma_f32 v238, v238, v206, v110
	v_sub_f32_e32 v239, v239, v142
	v_mul_f32_e32 v239, v239, v143
	v_fma_f32 v239, v239, v207, v111
	v_sub_f32_e32 v240, v240, v142
	v_mul_f32_e32 v240, v240, v143
	v_fma_f32 v240, v240, v208, v104
	v_sub_f32_e32 v241, v241, v142
	v_mul_f32_e32 v241, v241, v143
	v_fma_f32 v241, v241, v209, v105
	v_sub_f32_e32 v242, v242, v142
	v_mul_f32_e32 v242, v242, v143
	v_fma_f32 v242, v242, v210, v106
	v_sub_f32_e32 v243, v243, v142
	v_mul_f32_e32 v243, v243, v143
	v_fma_f32 v243, v243, v211, v107
	v_sub_f32_e32 v244, v244, v142
	v_mul_f32_e32 v244, v244, v143
	v_fma_f32 v244, v244, v212, v100
	v_sub_f32_e32 v245, v245, v142
	v_mul_f32_e32 v245, v245, v143
	v_fma_f32 v245, v245, v213, v101
	v_sub_f32_e32 v246, v246, v142
	v_mul_f32_e32 v246, v246, v143
	v_fma_f32 v246, v246, v214, v102
	v_sub_f32_e32 v247, v247, v142
	v_mul_f32_e32 v247, v247, v143
	v_fma_f32 v247, v247, v215, v103
	v_sub_f32_e32 v248, v248, v142
	v_mul_f32_e32 v248, v248, v143
	v_fma_f32 v248, v248, v216, v96
	v_sub_f32_e32 v249, v249, v142
	v_mul_f32_e32 v249, v249, v143
	v_fma_f32 v249, v249, v217, v97
	v_sub_f32_e32 v250, v250, v142
	v_mul_f32_e32 v250, v250, v143
	v_fma_f32 v250, v250, v218, v98
	v_sub_f32_e32 v251, v251, v142
	v_mul_f32_e32 v251, v251, v143
	v_fma_f32 v251, v251, v219, v99
	global_load_dwordx4 v[124:127], v169, s[72:73] offset:0
	global_load_dwordx4 v[120:123], v169, s[72:73] offset:64
	global_load_dwordx4 v[116:119], v169, s[72:73] offset:512
	global_load_dwordx4 v[112:115], v169, s[72:73] offset:576
	global_load_dwordx4 v[108:111], v170, s[72:73] offset:0
	global_load_dwordx4 v[104:107], v170, s[72:73] offset:64
	global_load_dwordx4 v[100:103], v170, s[72:73] offset:512
	global_load_dwordx4 v[96:99], v170, s[72:73] offset:576
	global_store_dwordx4 v167, v[220:223], s[72:73] offset:0
	global_store_dwordx4 v167, v[224:227], s[72:73] offset:64
	global_store_dwordx4 v167, v[228:231], s[72:73] offset:512
	global_store_dwordx4 v167, v[232:235], s[72:73] offset:576
	global_store_dwordx4 v168, v[236:239], s[72:73] offset:0
	global_store_dwordx4 v168, v[240:243], s[72:73] offset:64
	global_store_dwordx4 v168, v[244:247], s[72:73] offset:512
	global_store_dwordx4 v168, v[248:251], s[72:73] offset:576
	global_load_dwordx4 v[220:223], v171, s[72:73] offset:0
	global_load_dwordx4 v[224:227], v171, s[72:73] offset:64
	global_load_dwordx4 v[228:231], v171, s[72:73] offset:512
	global_load_dwordx4 v[232:235], v171, s[72:73] offset:576
	global_load_dwordx4 v[236:239], v172, s[72:73] offset:0
	global_load_dwordx4 v[240:243], v172, s[72:73] offset:64
	global_load_dwordx4 v[244:247], v172, s[72:73] offset:512
	global_load_dwordx4 v[248:251], v172, s[72:73] offset:576
	s_waitcnt vmcnt(0)
;     DI void operator()(const f32x4 (&acc)[2][2][4][2], const Unit& u, int wr, int wc, int fr, int fq) const {
;     ...
;                 const int row = u.pm * BM + ai * HALF + wr * 64 + m * 16 + fr;
;                 float mu = 0.f, rs = 1.f;
;                 if (pg) { const float2 st = RS[row]; mu = st.x; rs = st.y; }
; #pragma unroll
;                 for (int bj = 0; bj < 2; ++bj)
; #pragma unroll
;                     for (int n = 0; n < 2; ++n) {
;                         const int col = u.pn * BM + bj * HALF + wc * 32 + n * 16 + 4 * fq;
;                         float* xp = X + (size_t)row * DM + col;
;                         f32x4 x4 = *(const f32x4*)xp; const f32x4 g4 = *(const f32x4*)(g + col);
;                         if (pg) x4 = (x4 - mu) * rs * *(const f32x4*)(pg + col) + *(const f32x4*)(pb + col);
;                         *(f32x4*)xp = x4 * ALPHA + g4 * acc[ai][bj][m][n];
;                     }
	v_sub_f32_e32 v124, v124, v144
	v_mul_f32_e32 v124, v124, v145
	v_fma_f32 v124, v124, v204, v92
	v_sub_f32_e32 v125, v125, v144
	v_mul_f32_e32 v125, v125, v145
	v_fma_f32 v125, v125, v205, v93
	v_sub_f32_e32 v126, v126, v144
	v_mul_f32_e32 v126, v126, v145
	v_fma_f32 v126, v126, v206, v94
	v_sub_f32_e32 v127, v127, v144
	v_mul_f32_e32 v127, v127, v145
	v_fma_f32 v127, v127, v207, v95
	v_sub_f32_e32 v120, v120, v144
	v_mul_f32_e32 v120, v120, v145
	v_fma_f32 v120, v120, v208, v88
	v_sub_f32_e32 v121, v121, v144
	v_mul_f32_e32 v121, v121, v145
	v_fma_f32 v121, v121, v209, v89
	v_sub_f32_e32 v122, v122, v144
	v_mul_f32_e32 v122, v122, v145
	v_fma_f32 v122, v122, v210, v90
	v_sub_f32_e32 v123, v123, v144
	v_mul_f32_e32 v123, v123, v145
	v_fma_f32 v123, v123, v211, v91
	v_sub_f32_e32 v116, v116, v144
	v_mul_f32_e32 v116, v116, v145
	v_fma_f32 v116, v116, v212, v84
	v_sub_f32_e32 v117, v117, v144
	v_mul_f32_e32 v117, v117, v145
	v_fma_f32 v117, v117, v213, v85
	v_sub_f32_e32 v118, v118, v144
	v_mul_f32_e32 v118, v118, v145
	v_fma_f32 v118, v118, v214, v86
	v_sub_f32_e32 v119, v119, v144
	v_mul_f32_e32 v119, v119, v145
	v_fma_f32 v119, v119, v215, v87
	v_sub_f32_e32 v112, v112, v144
	v_mul_f32_e32 v112, v112, v145
	v_fma_f32 v112, v112, v216, v80
	v_sub_f32_e32 v113, v113, v144
	v_mul_f32_e32 v113, v113, v145
	v_fma_f32 v113, v113, v217, v81
	v_sub_f32_e32 v114, v114, v144
	v_mul_f32_e32 v114, v114, v145
	v_fma_f32 v114, v114, v218, v82
	v_sub_f32_e32 v115, v115, v144
	v_mul_f32_e32 v115, v115, v145
	v_fma_f32 v115, v115, v219, v83
	v_sub_f32_e32 v108, v108, v146
	v_mul_f32_e32 v108, v108, v147
	v_fma_f32 v108, v108, v204, v76
	v_sub_f32_e32 v109, v109, v146
	v_mul_f32_e32 v109, v109, v147
	v_fma_f32 v109, v109, v205, v77
	v_sub_f32_e32 v110, v110, v146
	v_mul_f32_e32 v110, v110, v147
	v_fma_f32 v110, v110, v206, v78
	v_sub_f32_e32 v111, v111, v146
	v_mul_f32_e32 v111, v111, v147
	v_fma_f32 v111, v111, v207, v79
	v_sub_f32_e32 v104, v104, v146
	v_mul_f32_e32 v104, v104, v147
	v_fma_f32 v104, v104, v208, v72
	v_sub_f32_e32 v105, v105, v146
	v_mul_f32_e32 v105, v105, v147
	v_fma_f32 v105, v105, v209, v73
	v_sub_f32_e32 v106, v106, v146
	v_mul_f32_e32 v106, v106, v147
	v_fma_f32 v106, v106, v210, v74
	v_sub_f32_e32 v107, v107, v146
	v_mul_f32_e32 v107, v107, v147
	v_fma_f32 v107, v107, v211, v75
	v_sub_f32_e32 v100, v100, v146
	v_mul_f32_e32 v100, v100, v147
	v_fma_f32 v100, v100, v212, v68
	v_sub_f32_e32 v101, v101, v146
	v_mul_f32_e32 v101, v101, v147
	v_fma_f32 v101, v101, v213, v69
	v_sub_f32_e32 v102, v102, v146
	v_mul_f32_e32 v102, v102, v147
	v_fma_f32 v102, v102, v214, v70
	v_sub_f32_e32 v103, v103, v146
	v_mul_f32_e32 v103, v103, v147
	v_fma_f32 v103, v103, v215, v71
	v_sub_f32_e32 v96, v96, v146
	v_mul_f32_e32 v96, v96, v147
	v_fma_f32 v96, v96, v216, v64
	v_sub_f32_e32 v97, v97, v146
	v_mul_f32_e32 v97, v97, v147
	v_fma_f32 v97, v97, v217, v65
	v_sub_f32_e32 v98, v98, v146
	v_mul_f32_e32 v98, v98, v147
	v_fma_f32 v98, v98, v218, v66
	v_sub_f32_e32 v99, v99, v146
	v_mul_f32_e32 v99, v99, v147
	v_fma_f32 v99, v99, v219, v67
	v_sub_f32_e32 v220, v220, v148
	v_mul_f32_e32 v220, v220, v149
	v_fma_f32 v220, v220, v204, v60
	v_sub_f32_e32 v221, v221, v148
	v_mul_f32_e32 v221, v221, v149
	v_fma_f32 v221, v221, v205, v61
	v_sub_f32_e32 v222, v222, v148
	v_mul_f32_e32 v222, v222, v149
	v_fma_f32 v222, v222, v206, v62
	v_sub_f32_e32 v223, v223, v148
	v_mul_f32_e32 v223, v223, v149
	v_fma_f32 v223, v223, v207, v63
	v_sub_f32_e32 v224, v224, v148
	v_mul_f32_e32 v224, v224, v149
	v_fma_f32 v224, v224, v208, v56
	v_sub_f32_e32 v225, v225, v148
	v_mul_f32_e32 v225, v225, v149
	v_fma_f32 v225, v225, v209, v57
	v_sub_f32_e32 v226, v226, v148
	v_mul_f32_e32 v226, v226, v149
	v_fma_f32 v226, v226, v210, v58
	v_sub_f32_e32 v227, v227, v148
	v_mul_f32_e32 v227, v227, v149
	v_fma_f32 v227, v227, v211, v59
	v_sub_f32_e32 v228, v228, v148
	v_mul_f32_e32 v228, v228, v149
	v_fma_f32 v228, v228, v212, v52
	v_sub_f32_e32 v229, v229, v148
	v_mul_f32_e32 v229, v229, v149
	v_fma_f32 v229, v229, v213, v53
	v_sub_f32_e32 v230, v230, v148
	v_mul_f32_e32 v230, v230, v149
	v_fma_f32 v230, v230, v214, v54
	v_sub_f32_e32 v231, v231, v148
	v_mul_f32_e32 v231, v231, v149
	v_fma_f32 v231, v231, v215, v55
	v_sub_f32_e32 v232, v232, v148
	v_mul_f32_e32 v232, v232, v149
	v_fma_f32 v232, v232, v216, v48
	v_sub_f32_e32 v233, v233, v148
	v_mul_f32_e32 v233, v233, v149
	v_fma_f32 v233, v233, v217, v49
	v_sub_f32_e32 v234, v234, v148
	v_mul_f32_e32 v234, v234, v149
	v_fma_f32 v234, v234, v218, v50
	v_sub_f32_e32 v235, v235, v148
	v_mul_f32_e32 v235, v235, v149
	v_fma_f32 v235, v235, v219, v51
	v_sub_f32_e32 v236, v236, v150
	v_mul_f32_e32 v236, v236, v151
	v_fma_f32 v236, v236, v204, v44
	v_sub_f32_e32 v237, v237, v150
	v_mul_f32_e32 v237, v237, v151
	v_fma_f32 v237, v237, v205, v45
	v_sub_f32_e32 v238, v238, v150
	v_mul_f32_e32 v238, v238, v151
	v_fma_f32 v238, v238, v206, v46
	v_sub_f32_e32 v239, v239, v150
	v_mul_f32_e32 v239, v239, v151
	v_fma_f32 v239, v239, v207, v47
	v_sub_f32_e32 v240, v240, v150
	v_mul_f32_e32 v240, v240, v151
	v_fma_f32 v240, v240, v208, v40
	v_sub_f32_e32 v241, v241, v150
	v_mul_f32_e32 v241, v241, v151
	v_fma_f32 v241, v241, v209, v41
	v_sub_f32_e32 v242, v242, v150
	v_mul_f32_e32 v242, v242, v151
	v_fma_f32 v242, v242, v210, v42
	v_sub_f32_e32 v243, v243, v150
	v_mul_f32_e32 v243, v243, v151
	v_fma_f32 v243, v243, v211, v43
	v_sub_f32_e32 v244, v244, v150
	v_mul_f32_e32 v244, v244, v151
	v_fma_f32 v244, v244, v212, v36
	v_sub_f32_e32 v245, v245, v150
	v_mul_f32_e32 v245, v245, v151
	v_fma_f32 v245, v245, v213, v37
;     DI void operator()(const f32x4 (&acc)[2][2][4][2], const Unit& u, int wr, int wc, int fr, int fq) const {
;     ...
;                 const int row = u.pm * BM + ai * HALF + wr * 64 + m * 16 + fr;
;                 float mu = 0.f, rs = 1.f;
;                 if (pg) { const float2 st = RS[row]; mu = st.x; rs = st.y; }
; #pragma unroll
;                 for (int bj = 0; bj < 2; ++bj)
; #pragma unroll
;                     for (int n = 0; n < 2; ++n) {
;                         const int col = u.pn * BM + bj * HALF + wc * 32 + n * 16 + 4 * fq;
;                         float* xp = X + (size_t)row * DM + col;
;                         f32x4 x4 = *(const f32x4*)xp; const f32x4 g4 = *(const f32x4*)(g + col);
;                         if (pg) x4 = (x4 - mu) * rs * *(const f32x4*)(pg + col) + *(const f32x4*)(pb + col);
;                         *(f32x4*)xp = x4 * ALPHA + g4 * acc[ai][bj][m][n];
;                     }
	v_sub_f32_e32 v246, v246, v150
	v_mul_f32_e32 v246, v246, v151
	v_fma_f32 v246, v246, v214, v38
	v_sub_f32_e32 v247, v247, v150
	v_mul_f32_e32 v247, v247, v151
	v_fma_f32 v247, v247, v215, v39
	v_sub_f32_e32 v248, v248, v150
	v_mul_f32_e32 v248, v248, v151
	v_fma_f32 v248, v248, v216, v32
	v_sub_f32_e32 v249, v249, v150
	v_mul_f32_e32 v249, v249, v151
	v_fma_f32 v249, v249, v217, v33
	v_sub_f32_e32 v250, v250, v150
	v_mul_f32_e32 v250, v250, v151
	v_fma_f32 v250, v250, v218, v34
	v_sub_f32_e32 v251, v251, v150
	v_mul_f32_e32 v251, v251, v151
	v_fma_f32 v251, v251, v219, v35
	global_load_dwordx4 v[92:95], v173, s[72:73] offset:0
	global_load_dwordx4 v[88:91], v173, s[72:73] offset:64
	global_load_dwordx4 v[84:87], v173, s[72:73] offset:512
	global_load_dwordx4 v[80:83], v173, s[72:73] offset:576
	global_load_dwordx4 v[76:79], v174, s[72:73] offset:0
	global_load_dwordx4 v[72:75], v174, s[72:73] offset:64
	global_load_dwordx4 v[68:71], v174, s[72:73] offset:512
	global_load_dwordx4 v[64:67], v174, s[72:73] offset:576
	global_store_dwordx4 v169, v[124:127], s[72:73] offset:0
	global_store_dwordx4 v169, v[120:123], s[72:73] offset:64
	global_store_dwordx4 v169, v[116:119], s[72:73] offset:512
	global_store_dwordx4 v169, v[112:115], s[72:73] offset:576
	global_store_dwordx4 v170, v[108:111], s[72:73] offset:0
	global_store_dwordx4 v170, v[104:107], s[72:73] offset:64
	global_store_dwordx4 v170, v[100:103], s[72:73] offset:512
	global_store_dwordx4 v170, v[96:99], s[72:73] offset:576
	global_store_dwordx4 v171, v[220:223], s[72:73] offset:0
	global_store_dwordx4 v171, v[224:227], s[72:73] offset:64
	global_store_dwordx4 v171, v[228:231], s[72:73] offset:512
	global_store_dwordx4 v171, v[232:235], s[72:73] offset:576
	global_store_dwordx4 v172, v[236:239], s[72:73] offset:0
	global_store_dwordx4 v172, v[240:243], s[72:73] offset:64
	global_store_dwordx4 v172, v[244:247], s[72:73] offset:512
	global_store_dwordx4 v172, v[248:251], s[72:73] offset:576
	s_waitcnt vmcnt(16)
	v_sub_f32_e32 v92, v92, v152
	v_mul_f32_e32 v92, v92, v153
	v_fma_f32 v92, v92, v204, v28
	v_sub_f32_e32 v93, v93, v152
	v_mul_f32_e32 v93, v93, v153
	v_fma_f32 v93, v93, v205, v29
	v_sub_f32_e32 v94, v94, v152
	v_mul_f32_e32 v94, v94, v153
	v_fma_f32 v94, v94, v206, v30
	v_sub_f32_e32 v95, v95, v152
	v_mul_f32_e32 v95, v95, v153
	v_fma_f32 v95, v95, v207, v31
	v_sub_f32_e32 v88, v88, v152
	v_mul_f32_e32 v88, v88, v153
	v_fma_f32 v88, v88, v208, v24
	v_sub_f32_e32 v89, v89, v152
	v_mul_f32_e32 v89, v89, v153
	v_fma_f32 v89, v89, v209, v25
	v_sub_f32_e32 v90, v90, v152
	v_mul_f32_e32 v90, v90, v153
	v_fma_f32 v90, v90, v210, v26
	v_sub_f32_e32 v91, v91, v152
	v_mul_f32_e32 v91, v91, v153
	v_fma_f32 v91, v91, v211, v27
	v_sub_f32_e32 v84, v84, v152
	v_mul_f32_e32 v84, v84, v153
	v_fma_f32 v84, v84, v212, v20
	v_sub_f32_e32 v85, v85, v152
	v_mul_f32_e32 v85, v85, v153
	v_fma_f32 v85, v85, v213, v21
	v_sub_f32_e32 v86, v86, v152
	v_mul_f32_e32 v86, v86, v153
	v_fma_f32 v86, v86, v214, v22
	v_sub_f32_e32 v87, v87, v152
	v_mul_f32_e32 v87, v87, v153
	v_fma_f32 v87, v87, v215, v23
	v_sub_f32_e32 v80, v80, v152
	v_mul_f32_e32 v80, v80, v153
	v_fma_f32 v80, v80, v216, v12
	v_sub_f32_e32 v81, v81, v152
	v_mul_f32_e32 v81, v81, v153
	v_fma_f32 v81, v81, v217, v13
	v_sub_f32_e32 v82, v82, v152
	v_mul_f32_e32 v82, v82, v153
	v_fma_f32 v82, v82, v218, v14
	v_sub_f32_e32 v83, v83, v152
	v_mul_f32_e32 v83, v83, v153
	v_fma_f32 v83, v83, v219, v15
	v_sub_f32_e32 v76, v76, v164
	v_mul_f32_e32 v76, v76, v165
	v_fma_f32 v76, v76, v204, v16
	v_sub_f32_e32 v77, v77, v164
	v_mul_f32_e32 v77, v77, v165
	v_fma_f32 v77, v77, v205, v17
	v_sub_f32_e32 v78, v78, v164
	v_mul_f32_e32 v78, v78, v165
	v_fma_f32 v78, v78, v206, v18
	v_sub_f32_e32 v79, v79, v164
	v_mul_f32_e32 v79, v79, v165
	v_fma_f32 v79, v79, v207, v19
	v_sub_f32_e32 v72, v72, v164
	v_mul_f32_e32 v72, v72, v165
	v_fma_f32 v72, v72, v208, v8
	v_sub_f32_e32 v73, v73, v164
	v_mul_f32_e32 v73, v73, v165
	v_fma_f32 v73, v73, v209, v9
	v_sub_f32_e32 v74, v74, v164
	v_mul_f32_e32 v74, v74, v165
	v_fma_f32 v74, v74, v210, v10
	v_sub_f32_e32 v75, v75, v164
	v_mul_f32_e32 v75, v75, v165
	v_fma_f32 v75, v75, v211, v11
	v_sub_f32_e32 v68, v68, v164
	v_mul_f32_e32 v68, v68, v165
	v_fma_f32 v68, v68, v212, v4
	v_sub_f32_e32 v69, v69, v164
	v_mul_f32_e32 v69, v69, v165
	v_fma_f32 v69, v69, v213, v5
	v_sub_f32_e32 v70, v70, v164
	v_mul_f32_e32 v70, v70, v165
	v_fma_f32 v70, v70, v214, v6
	v_sub_f32_e32 v71, v71, v164
	v_mul_f32_e32 v71, v71, v165
	v_fma_f32 v71, v71, v215, v7
	v_sub_f32_e32 v64, v64, v164
	v_mul_f32_e32 v64, v64, v165
	v_fma_f32 v64, v64, v216, v0
	v_sub_f32_e32 v65, v65, v164
	v_mul_f32_e32 v65, v65, v165
	v_fma_f32 v65, v65, v217, v1
	v_sub_f32_e32 v66, v66, v164
	v_mul_f32_e32 v66, v66, v165
	v_fma_f32 v66, v66, v218, v2
	v_sub_f32_e32 v67, v67, v164
	v_mul_f32_e32 v67, v67, v165
	v_fma_f32 v67, v67, v219, v3
	global_store_dwordx4 v173, v[92:95], s[72:73] offset:0
	global_store_dwordx4 v173, v[88:91], s[72:73] offset:64
	global_store_dwordx4 v173, v[84:87], s[72:73] offset:512
	global_store_dwordx4 v173, v[80:83], s[72:73] offset:576
	global_store_dwordx4 v174, v[76:79], s[72:73] offset:0
	global_store_dwordx4 v174, v[72:75], s[72:73] offset:64
	global_store_dwordx4 v174, v[68:71], s[72:73] offset:512
	global_store_dwordx4 v174, v[64:67], s[72:73] offset:576
	s_mov_b32 s60, s57
	s_mov_b64 s[22:23], s[0:1]
	s_and_b64 vcc, exec, s[2:3]
	s_mov_b32 s59, s58
	s_mov_b64 s[20:21], s[4:5]
	s_cbranch_vccz .LBB0_3102
	s_waitcnt vmcnt(0)
	s_cmpk_gt_u32 s19, 0xff
	s_cbranch_scc1 .LBB0_3117
	s_barrier
